# V phase: record blocks staged into LDS by DMA, three gather buffers (two units of lead)
# speedup vs baseline: 1.1984x; 1.0253x over previous
; __device__ __forceinline__ void phase5(const Params& p, char* smem, const bool store_x = true) {
;     ...
; #pragma unroll
;       for (int sl = 0; sl < 7; sl++) {
;         if (key[sl] >= m) {
;           int pos = atomicAdd(&wcnt[hd], 1);
;           int ia = ti[ij[sl] >> 4], ib = ti[16 + (ij[sl] & 15)];
;           widx[hd * 16 + pos] = ia * 128 + ib;
;           wgate[hd * 16 + pos] = ev[sl] * inv;
;         }
;       }
.LBB0_1512:
	v_mbcnt_lo_u32_b32 v0, -1, 0
	v_mbcnt_hi_u32_b32 v0, -1, v0
	v_lshl_add_u32 v1, v0, 3, v176
	ds_read_b64 v[2:3], v1
	ds_read_b64 v[4:5], v1 offset:1024
	s_add_u32 s98, s80, 0x3bb5000
	s_addc_u32 s99, s81, 0
	v_lshl_add_u32 v6, v0, 3, v200
	v_lshrrev_b32_e32 v7, 8, v200
	v_add_u32_e32 v7, 0x1100000, v7
	v_mov_b32_e32 v20, 0
	s_waitcnt lgkmcnt(0)
	v_lshlrev_b32_e32 v16, 7, v2
	v_lshlrev_b32_e32 v17, 7, v3
	global_store_dwordx2 v6, v[16:17], s[98:99]
	global_store_dwordx2 v6, v[4:5], s[98:99] offset:512
	s_mov_b64 exec, 1
	global_store_dword v7, v20, s[98:99]
	s_mov_b64 exec, -1
	v_mov_b32_e32 v105, 0x358637bd
	v_accvgpr_read_b32 v96, a12
	v_accvgpr_read_b32 v97, a13
	v_accvgpr_read_b32 v98, a14
	v_accvgpr_read_b32 v99, a15
	v_accvgpr_read_b32 v100, a8
	v_accvgpr_read_b32 v101, a9
	v_accvgpr_read_b32 v102, a10
	v_accvgpr_read_b32 v103, a11
	v_mov_b32_e32 v104, v240
	s_and_b64 vcc, exec, s[34:35]
	s_cbranch_vccnz .Lp5a_done
	s_branch .LBB0_1482

; #define P5_LOAD(A, TAB, j0)                                                                \
;   _Pragma("unroll") for (int q = 0; q < 16; q++) {                                         \
;     A[q] = ((const uint4*)((TAB) + (size_t)widx[(j0) + q] * 1024))[lane];                  \
;   }
; __device__ __forceinline__ void phase5(const Params& p, char* smem, const bool store_x = true) {
;     ...
; #pragma unroll 1
;     for (int j0 = 0; j0 < 128; j0 += 32) {
;       P5_LOAD(A1, EV, j0 + 16)
;       P5_COMPUTE_V(A0, j0)
;       if (j0 + 32 < 128) { P5_LOAD(A0, EV, j0 + 32) }
;       P5_COMPUTE_V(A1, j0 + 16)
;     }
.Lp5v_start:
	v_mbcnt_lo_u32_b32 v0, -1, 0
	v_mbcnt_hi_u32_b32 v0, -1, v0
	v_accvgpr_read_b32 v4, a129
	s_and_b32 s0, s96, 7
	s_lshr_b32 s1, s96, 3
	v_and_b32_e32 v1, 7, v0
	v_lshrrev_b32_e32 v2, 3, v0
	v_lshlrev_b32_e32 v3, 1, v2
	v_lshl_add_u32 v3, v1, 4, v3
	v_lshlrev_b32_e32 v3, 2, v3
	v_lshlrev_b32_e32 v1, 4, v1
	v_lshlrev_b32_e32 v2, 6, v2
	v_readfirstlane_b32 s8, v4
	s_lshl_b32 s17, s8, 13
	v_add_u32_e32 v2, s17, v2
	s_lshl_b32 s10, s1, 2
	s_add_u32 s8, s8, s10
	s_lshr_b32 s9, s82, 1
	s_lshl_b32 s10, s0, 21
	s_add_u32 s2, s80, 0xbf35000
	s_addc_u32 s3, s81, 0
	s_add_u32 s2, s2, s10
	s_addc_u32 s3, s3, 0
	s_add_u32 s4, s80, 0x3bb5000
	s_addc_u32 s5, s81, 0
	s_lshl_b32 s10, s0, 9
	s_add_u32 s6, s78, s10
	s_addc_u32 s7, s79, 0
	s_movk_i32 s13, 0x41ff
	s_mov_b32 s14, 0xff00ff00
	s_mov_b32 s15, 0xff00ff00
	s_mov_b32 s16, 0
	s_mov_b32 s19, 0
	v_lshlrev_b32_e32 v9, 4, v0
	v_mov_b32_e32 v59, s5
	v_add_co_u32_e32 v58, vcc, s4, v9
	s_nop 1
	v_addc_co_u32_e32 v59, vcc, 0, v59, vcc
	s_mul_i32 s20, s9, 1
	s_mul_i32 s21, s9, 2
	s_mul_i32 s22, s9, 3
	s_mul_i32 s23, s9, 4
	s_mul_i32 s24, s9, 5
	s_mul_i32 s25, s9, 6
	s_mul_i32 s26, s9, 7
	s_mul_i32 s27, s9, 8
	s_min_u32 s10, s8, s13
	s_lshl_b32 s18, s10, 10
	s_add_u32 s11, s16, 0
	s_and_b32 s11, s11, 7
	s_lshl_b32 s11, s11, 10
	s_add_u32 s11, s11, s17
	s_mov_b32 m0, s11
	v_lshl_add_u64 v[4:5], v[58:59], 0, s[18:19]
	global_load_lds_dwordx4 v[4:5], off
	s_add_u32 s10, s8, s20
	s_min_u32 s10, s10, s13
	s_lshl_b32 s18, s10, 10
	s_add_u32 s11, s16, 1
	s_and_b32 s11, s11, 7
	s_lshl_b32 s11, s11, 10
	s_add_u32 s11, s11, s17
	s_mov_b32 m0, s11
	v_lshl_add_u64 v[4:5], v[58:59], 0, s[18:19]
	global_load_lds_dwordx4 v[4:5], off
	s_add_u32 s10, s8, s21
	s_min_u32 s10, s10, s13
	s_lshl_b32 s18, s10, 10
	s_add_u32 s11, s16, 2
	s_and_b32 s11, s11, 7
	s_lshl_b32 s11, s11, 10
	s_add_u32 s11, s11, s17
	s_mov_b32 m0, s11
	v_lshl_add_u64 v[4:5], v[58:59], 0, s[18:19]
	global_load_lds_dwordx4 v[4:5], off
	s_add_u32 s10, s8, s22
	s_min_u32 s10, s10, s13
	s_lshl_b32 s18, s10, 10
	s_add_u32 s11, s16, 3
	s_and_b32 s11, s11, 7
	s_lshl_b32 s11, s11, 10
	s_add_u32 s11, s11, s17
	s_mov_b32 m0, s11
	v_lshl_add_u64 v[4:5], v[58:59], 0, s[18:19]
	global_load_lds_dwordx4 v[4:5], off
	s_add_u32 s10, s8, s23
	s_min_u32 s10, s10, s13
	s_lshl_b32 s18, s10, 10
	s_add_u32 s11, s16, 4
	s_and_b32 s11, s11, 7
	s_lshl_b32 s11, s11, 10
	s_add_u32 s11, s11, s17
	s_mov_b32 m0, s11
	v_lshl_add_u64 v[4:5], v[58:59], 0, s[18:19]
	global_load_lds_dwordx4 v[4:5], off
	s_add_u32 s10, s8, s24
	s_min_u32 s10, s10, s13
	s_lshl_b32 s18, s10, 10
	s_add_u32 s11, s16, 5
	s_and_b32 s11, s11, 7
	s_lshl_b32 s11, s11, 10
	s_add_u32 s11, s11, s17
	s_mov_b32 m0, s11
	v_lshl_add_u64 v[4:5], v[58:59], 0, s[18:19]
	global_load_lds_dwordx4 v[4:5], off
	s_waitcnt vmcnt(0)
	s_add_u32 s11, s16, 0
	s_and_b32 s11, s11, 7
	s_lshl_b32 s11, s11, 10
	v_add_u32_e32 v8, s11, v2
	ds_read_b128 v[10:13], v8 offset:0
	ds_read_b128 v[14:17], v8 offset:16
	ds_read_b128 v[18:21], v8 offset:32
	ds_read_b128 v[22:25], v8 offset:48
	s_min_u32 s10, s8, s13
	s_lshl_b32 s11, s10, 12
	v_add_u32_e32 v6, s11, v3
	global_load_dwordx2 v[50:51], v6, s[6:7]
	s_waitcnt lgkmcnt(0)
	v_add_u32_e32 v10, v10, v1
	global_load_dwordx4 v[60:63], v10, s[2:3]
	v_add_u32_e32 v11, v11, v1
	global_load_dwordx4 v[64:67], v11, s[2:3]
	v_add_u32_e32 v12, v12, v1
	global_load_dwordx4 v[68:71], v12, s[2:3]
	v_add_u32_e32 v13, v13, v1
	global_load_dwordx4 v[72:75], v13, s[2:3]
	v_add_u32_e32 v14, v14, v1
	global_load_dwordx4 v[76:79], v14, s[2:3]
	v_add_u32_e32 v15, v15, v1
	global_load_dwordx4 v[80:83], v15, s[2:3]
	v_add_u32_e32 v16, v16, v1
	global_load_dwordx4 v[84:87], v16, s[2:3]
	v_add_u32_e32 v17, v17, v1
	global_load_dwordx4 v[88:91], v17, s[2:3]
	v_add_u32_e32 v18, v18, v1
	global_load_dwordx4 v[92:95], v18, s[2:3]
	v_add_u32_e32 v19, v19, v1
	global_load_dwordx4 v[96:99], v19, s[2:3]
	v_add_u32_e32 v20, v20, v1
	global_load_dwordx4 v[100:103], v20, s[2:3]
	v_add_u32_e32 v21, v21, v1
	global_load_dwordx4 v[104:107], v21, s[2:3]
	v_add_u32_e32 v22, v22, v1
	global_load_dwordx4 v[108:111], v22, s[2:3]
	v_add_u32_e32 v23, v23, v1
	global_load_dwordx4 v[112:115], v23, s[2:3]
	v_add_u32_e32 v24, v24, v1
	global_load_dwordx4 v[116:119], v24, s[2:3]
	v_add_u32_e32 v25, v25, v1
	global_load_dwordx4 v[120:123], v25, s[2:3]
	global_load_dword v56, v6, s[6:7]
	global_load_dword v56, v6, s[6:7]
	global_load_dword v56, v6, s[6:7]
	s_add_u32 s11, s16, 1
	s_and_b32 s11, s11, 7
	s_lshl_b32 s11, s11, 10
	v_add_u32_e32 v8, s11, v2
	ds_read_b128 v[10:13], v8 offset:0
	ds_read_b128 v[14:17], v8 offset:16
	ds_read_b128 v[18:21], v8 offset:32
	ds_read_b128 v[22:25], v8 offset:48
	s_add_u32 s10, s8, s20
	s_min_u32 s10, s10, s13
	s_lshl_b32 s11, s10, 12
	v_add_u32_e32 v6, s11, v3
	global_load_dwordx2 v[52:53], v6, s[6:7]
	s_waitcnt lgkmcnt(0)
	v_add_u32_e32 v10, v10, v1
	global_load_dwordx4 v[124:127], v10, s[2:3]
	v_add_u32_e32 v11, v11, v1
	global_load_dwordx4 v[128:131], v11, s[2:3]
	v_add_u32_e32 v12, v12, v1
	global_load_dwordx4 v[132:135], v12, s[2:3]
	v_add_u32_e32 v13, v13, v1
	global_load_dwordx4 v[136:139], v13, s[2:3]
	v_add_u32_e32 v14, v14, v1
	global_load_dwordx4 v[140:143], v14, s[2:3]
	v_add_u32_e32 v15, v15, v1
	global_load_dwordx4 v[144:147], v15, s[2:3]
	v_add_u32_e32 v16, v16, v1
	global_load_dwordx4 v[148:151], v16, s[2:3]
	v_add_u32_e32 v17, v17, v1
	global_load_dwordx4 v[152:155], v17, s[2:3]
	v_add_u32_e32 v18, v18, v1
	global_load_dwordx4 v[156:159], v18, s[2:3]
	v_add_u32_e32 v19, v19, v1
	global_load_dwordx4 v[160:163], v19, s[2:3]
	v_add_u32_e32 v20, v20, v1
	global_load_dwordx4 v[164:167], v20, s[2:3]
	v_add_u32_e32 v21, v21, v1
	global_load_dwordx4 v[168:171], v21, s[2:3]
	v_add_u32_e32 v22, v22, v1
	global_load_dwordx4 v[172:175], v22, s[2:3]
	v_add_u32_e32 v23, v23, v1
	global_load_dwordx4 v[176:179], v23, s[2:3]
	v_add_u32_e32 v24, v24, v1
	global_load_dwordx4 v[180:183], v24, s[2:3]
	v_add_u32_e32 v25, v25, v1
	global_load_dwordx4 v[184:187], v25, s[2:3]
	global_load_dword v56, v6, s[6:7]
	global_load_dword v56, v6, s[6:7]
.Lp5v_loop:
	s_add_u32 s10, s8, s25
	s_min_u32 s10, s10, s13
	s_lshl_b32 s18, s10, 10
	s_add_u32 s11, s16, 6
	s_and_b32 s11, s11, 7
	s_lshl_b32 s11, s11, 10
	s_add_u32 s11, s11, s17
	s_mov_b32 m0, s11
	v_lshl_add_u64 v[4:5], v[58:59], 0, s[18:19]
	global_load_lds_dwordx4 v[4:5], off
	s_add_u32 s11, s16, 2
	s_and_b32 s11, s11, 7
	s_lshl_b32 s11, s11, 10
	v_add_u32_e32 v8, s11, v2
	ds_read_b128 v[10:13], v8 offset:0
	ds_read_b128 v[14:17], v8 offset:16
	ds_read_b128 v[18:21], v8 offset:32
	ds_read_b128 v[22:25], v8 offset:48
	s_add_u32 s10, s8, s21
	s_min_u32 s10, s10, s13
	s_lshl_b32 s11, s10, 12
	v_add_u32_e32 v6, s11, v3
	global_load_dwordx2 v[54:55], v6, s[6:7]
	s_waitcnt lgkmcnt(0)
	v_add_u32_e32 v10, v10, v1
	global_load_dwordx4 v[188:191], v10, s[2:3]
	v_add_u32_e32 v11, v11, v1
	global_load_dwordx4 v[192:195], v11, s[2:3]
	v_add_u32_e32 v12, v12, v1
	global_load_dwordx4 v[196:199], v12, s[2:3]
	v_add_u32_e32 v13, v13, v1
	global_load_dwordx4 v[200:203], v13, s[2:3]
	v_add_u32_e32 v14, v14, v1
	global_load_dwordx4 v[204:207], v14, s[2:3]
	v_add_u32_e32 v15, v15, v1
	global_load_dwordx4 v[208:211], v15, s[2:3]
	v_add_u32_e32 v16, v16, v1
	global_load_dwordx4 v[212:215], v16, s[2:3]
	v_add_u32_e32 v17, v17, v1
	global_load_dwordx4 v[216:219], v17, s[2:3]
	v_add_u32_e32 v18, v18, v1
	global_load_dwordx4 v[220:223], v18, s[2:3]
	v_add_u32_e32 v19, v19, v1
	global_load_dwordx4 v[224:227], v19, s[2:3]
	v_add_u32_e32 v20, v20, v1
	global_load_dwordx4 v[228:231], v20, s[2:3]
	v_add_u32_e32 v21, v21, v1
	global_load_dwordx4 v[232:235], v21, s[2:3]
	v_add_u32_e32 v22, v22, v1
	global_load_dwordx4 v[236:239], v22, s[2:3]
	v_add_u32_e32 v23, v23, v1
	global_load_dwordx4 v[240:243], v23, s[2:3]
	v_add_u32_e32 v24, v24, v1
	global_load_dwordx4 v[244:247], v24, s[2:3]
	v_add_u32_e32 v25, v25, v1
	global_load_dwordx4 v[248:251], v25, s[2:3]
	s_add_u32 s11, s16, 0
	s_and_b32 s11, s11, 7
	s_lshl_b32 s11, s11, 10
	v_add_u32_e32 v8, s11, v2
	ds_read_b128 v[10:13], v8 offset:512
	ds_read_b128 v[14:17], v8 offset:528
	ds_read_b128 v[18:21], v8 offset:544
	ds_read_b128 v[22:25], v8 offset:560
	s_mov_b32 s12, s8
	s_waitcnt vmcnt(40) lgkmcnt(0)
	s_cmp_lt_u32 s12, 0x4200
	s_cbranch_scc0 .Lp5v_skip0
	v_cvt_pk_f32_fp8_e32 v[42:43], v60
	v_cvt_pk_f32_fp8_sdwa v[44:45], v60 src0_sel:WORD_1
	v_pk_mul_f32 v[26:27], v[42:43], v[10:11] op_sel_hi:[1,0]
	v_pk_mul_f32 v[28:29], v[44:45], v[10:11] op_sel_hi:[1,0]
	v_cvt_pk_f32_fp8_e32 v[46:47], v61
	v_cvt_pk_f32_fp8_sdwa v[48:49], v61 src0_sel:WORD_1
	v_pk_mul_f32 v[30:31], v[46:47], v[10:11] op_sel_hi:[1,0]
	v_pk_mul_f32 v[32:33], v[48:49], v[10:11] op_sel_hi:[1,0]
	v_cvt_pk_f32_fp8_e32 v[42:43], v62
	v_cvt_pk_f32_fp8_sdwa v[44:45], v62 src0_sel:WORD_1
	v_pk_mul_f32 v[34:35], v[42:43], v[10:11] op_sel_hi:[1,0]
	v_pk_mul_f32 v[36:37], v[44:45], v[10:11] op_sel_hi:[1,0]
	v_cvt_pk_f32_fp8_e32 v[46:47], v63
	v_cvt_pk_f32_fp8_sdwa v[48:49], v63 src0_sel:WORD_1
	v_pk_mul_f32 v[38:39], v[46:47], v[10:11] op_sel_hi:[1,0]
	v_pk_mul_f32 v[40:41], v[48:49], v[10:11] op_sel_hi:[1,0]
	v_cvt_pk_f32_fp8_e32 v[42:43], v64
	v_cvt_pk_f32_fp8_sdwa v[44:45], v64 src0_sel:WORD_1
	v_pk_fma_f32 v[26:27], v[42:43], v[10:11], v[26:27] op_sel:[0,1,0] op_sel_hi:[1,1,1]
	v_pk_fma_f32 v[28:29], v[44:45], v[10:11], v[28:29] op_sel:[0,1,0] op_sel_hi:[1,1,1]
	v_cvt_pk_f32_fp8_e32 v[46:47], v65
	v_cvt_pk_f32_fp8_sdwa v[48:49], v65 src0_sel:WORD_1
	v_pk_fma_f32 v[30:31], v[46:47], v[10:11], v[30:31] op_sel:[0,1,0] op_sel_hi:[1,1,1]
	v_pk_fma_f32 v[32:33], v[48:49], v[10:11], v[32:33] op_sel:[0,1,0] op_sel_hi:[1,1,1]
	v_cvt_pk_f32_fp8_e32 v[42:43], v66
	v_cvt_pk_f32_fp8_sdwa v[44:45], v66 src0_sel:WORD_1
	v_pk_fma_f32 v[34:35], v[42:43], v[10:11], v[34:35] op_sel:[0,1,0] op_sel_hi:[1,1,1]
	v_pk_fma_f32 v[36:37], v[44:45], v[10:11], v[36:37] op_sel:[0,1,0] op_sel_hi:[1,1,1]
	v_cvt_pk_f32_fp8_e32 v[46:47], v67
	v_cvt_pk_f32_fp8_sdwa v[48:49], v67 src0_sel:WORD_1
	v_pk_fma_f32 v[38:39], v[46:47], v[10:11], v[38:39] op_sel:[0,1,0] op_sel_hi:[1,1,1]
	v_pk_fma_f32 v[40:41], v[48:49], v[10:11], v[40:41] op_sel:[0,1,0] op_sel_hi:[1,1,1]
	v_cvt_pk_f32_fp8_e32 v[42:43], v68
	v_cvt_pk_f32_fp8_sdwa v[44:45], v68 src0_sel:WORD_1
	v_pk_fma_f32 v[26:27], v[42:43], v[12:13], v[26:27] op_sel_hi:[1,0,1]
	v_pk_fma_f32 v[28:29], v[44:45], v[12:13], v[28:29] op_sel_hi:[1,0,1]
	v_cvt_pk_f32_fp8_e32 v[46:47], v69
	v_cvt_pk_f32_fp8_sdwa v[48:49], v69 src0_sel:WORD_1
	v_pk_fma_f32 v[30:31], v[46:47], v[12:13], v[30:31] op_sel_hi:[1,0,1]
	v_pk_fma_f32 v[32:33], v[48:49], v[12:13], v[32:33] op_sel_hi:[1,0,1]
	v_cvt_pk_f32_fp8_e32 v[42:43], v70
	v_cvt_pk_f32_fp8_sdwa v[44:45], v70 src0_sel:WORD_1
	v_pk_fma_f32 v[34:35], v[42:43], v[12:13], v[34:35] op_sel_hi:[1,0,1]
	v_pk_fma_f32 v[36:37], v[44:45], v[12:13], v[36:37] op_sel_hi:[1,0,1]
	v_cvt_pk_f32_fp8_e32 v[46:47], v71
	v_cvt_pk_f32_fp8_sdwa v[48:49], v71 src0_sel:WORD_1
	v_pk_fma_f32 v[38:39], v[46:47], v[12:13], v[38:39] op_sel_hi:[1,0,1]
	v_pk_fma_f32 v[40:41], v[48:49], v[12:13], v[40:41] op_sel_hi:[1,0,1]
	v_cvt_pk_f32_fp8_e32 v[42:43], v72
	v_cvt_pk_f32_fp8_sdwa v[44:45], v72 src0_sel:WORD_1
	v_pk_fma_f32 v[26:27], v[42:43], v[12:13], v[26:27] op_sel:[0,1,0] op_sel_hi:[1,1,1]
	v_pk_fma_f32 v[28:29], v[44:45], v[12:13], v[28:29] op_sel:[0,1,0] op_sel_hi:[1,1,1]
	v_cvt_pk_f32_fp8_e32 v[46:47], v73
	v_cvt_pk_f32_fp8_sdwa v[48:49], v73 src0_sel:WORD_1
	v_pk_fma_f32 v[30:31], v[46:47], v[12:13], v[30:31] op_sel:[0,1,0] op_sel_hi:[1,1,1]
	v_pk_fma_f32 v[32:33], v[48:49], v[12:13], v[32:33] op_sel:[0,1,0] op_sel_hi:[1,1,1]
	v_cvt_pk_f32_fp8_e32 v[42:43], v74
	v_cvt_pk_f32_fp8_sdwa v[44:45], v74 src0_sel:WORD_1
	v_pk_fma_f32 v[34:35], v[42:43], v[12:13], v[34:35] op_sel:[0,1,0] op_sel_hi:[1,1,1]
	v_pk_fma_f32 v[36:37], v[44:45], v[12:13], v[36:37] op_sel:[0,1,0] op_sel_hi:[1,1,1]
	v_cvt_pk_f32_fp8_e32 v[46:47], v75
	v_cvt_pk_f32_fp8_sdwa v[48:49], v75 src0_sel:WORD_1
	v_pk_fma_f32 v[38:39], v[46:47], v[12:13], v[38:39] op_sel:[0,1,0] op_sel_hi:[1,1,1]
	v_pk_fma_f32 v[40:41], v[48:49], v[12:13], v[40:41] op_sel:[0,1,0] op_sel_hi:[1,1,1]
	v_cvt_pk_f32_fp8_e32 v[42:43], v76
	v_cvt_pk_f32_fp8_sdwa v[44:45], v76 src0_sel:WORD_1
	v_pk_fma_f32 v[26:27], v[42:43], v[14:15], v[26:27] op_sel_hi:[1,0,1]
	v_pk_fma_f32 v[28:29], v[44:45], v[14:15], v[28:29] op_sel_hi:[1,0,1]
	v_cvt_pk_f32_fp8_e32 v[46:47], v77
	v_cvt_pk_f32_fp8_sdwa v[48:49], v77 src0_sel:WORD_1
	v_pk_fma_f32 v[30:31], v[46:47], v[14:15], v[30:31] op_sel_hi:[1,0,1]
	v_pk_fma_f32 v[32:33], v[48:49], v[14:15], v[32:33] op_sel_hi:[1,0,1]
	v_cvt_pk_f32_fp8_e32 v[42:43], v78
	v_cvt_pk_f32_fp8_sdwa v[44:45], v78 src0_sel:WORD_1
	v_pk_fma_f32 v[34:35], v[42:43], v[14:15], v[34:35] op_sel_hi:[1,0,1]
	v_pk_fma_f32 v[36:37], v[44:45], v[14:15], v[36:37] op_sel_hi:[1,0,1]
	v_cvt_pk_f32_fp8_e32 v[46:47], v79
	v_cvt_pk_f32_fp8_sdwa v[48:49], v79 src0_sel:WORD_1
	v_pk_fma_f32 v[38:39], v[46:47], v[14:15], v[38:39] op_sel_hi:[1,0,1]
	v_pk_fma_f32 v[40:41], v[48:49], v[14:15], v[40:41] op_sel_hi:[1,0,1]
	v_cvt_pk_f32_fp8_e32 v[42:43], v80
	v_cvt_pk_f32_fp8_sdwa v[44:45], v80 src0_sel:WORD_1
	v_pk_fma_f32 v[26:27], v[42:43], v[14:15], v[26:27] op_sel:[0,1,0] op_sel_hi:[1,1,1]
	v_pk_fma_f32 v[28:29], v[44:45], v[14:15], v[28:29] op_sel:[0,1,0] op_sel_hi:[1,1,1]
	v_cvt_pk_f32_fp8_e32 v[46:47], v81
	v_cvt_pk_f32_fp8_sdwa v[48:49], v81 src0_sel:WORD_1
	v_pk_fma_f32 v[30:31], v[46:47], v[14:15], v[30:31] op_sel:[0,1,0] op_sel_hi:[1,1,1]
	v_pk_fma_f32 v[32:33], v[48:49], v[14:15], v[32:33] op_sel:[0,1,0] op_sel_hi:[1,1,1]
	v_cvt_pk_f32_fp8_e32 v[42:43], v82
	v_cvt_pk_f32_fp8_sdwa v[44:45], v82 src0_sel:WORD_1
	v_pk_fma_f32 v[34:35], v[42:43], v[14:15], v[34:35] op_sel:[0,1,0] op_sel_hi:[1,1,1]
	v_pk_fma_f32 v[36:37], v[44:45], v[14:15], v[36:37] op_sel:[0,1,0] op_sel_hi:[1,1,1]
	v_cvt_pk_f32_fp8_e32 v[46:47], v83
	v_cvt_pk_f32_fp8_sdwa v[48:49], v83 src0_sel:WORD_1
	v_pk_fma_f32 v[38:39], v[46:47], v[14:15], v[38:39] op_sel:[0,1,0] op_sel_hi:[1,1,1]
	v_pk_fma_f32 v[40:41], v[48:49], v[14:15], v[40:41] op_sel:[0,1,0] op_sel_hi:[1,1,1]
	v_cvt_pk_f32_fp8_e32 v[42:43], v84
	v_cvt_pk_f32_fp8_sdwa v[44:45], v84 src0_sel:WORD_1
	v_pk_fma_f32 v[26:27], v[42:43], v[16:17], v[26:27] op_sel_hi:[1,0,1]
	v_pk_fma_f32 v[28:29], v[44:45], v[16:17], v[28:29] op_sel_hi:[1,0,1]
	v_cvt_pk_f32_fp8_e32 v[46:47], v85
	v_cvt_pk_f32_fp8_sdwa v[48:49], v85 src0_sel:WORD_1
	v_pk_fma_f32 v[30:31], v[46:47], v[16:17], v[30:31] op_sel_hi:[1,0,1]
	v_pk_fma_f32 v[32:33], v[48:49], v[16:17], v[32:33] op_sel_hi:[1,0,1]
	v_cvt_pk_f32_fp8_e32 v[42:43], v86
	v_cvt_pk_f32_fp8_sdwa v[44:45], v86 src0_sel:WORD_1
	v_pk_fma_f32 v[34:35], v[42:43], v[16:17], v[34:35] op_sel_hi:[1,0,1]
	v_pk_fma_f32 v[36:37], v[44:45], v[16:17], v[36:37] op_sel_hi:[1,0,1]
	v_cvt_pk_f32_fp8_e32 v[46:47], v87
	v_cvt_pk_f32_fp8_sdwa v[48:49], v87 src0_sel:WORD_1
	v_pk_fma_f32 v[38:39], v[46:47], v[16:17], v[38:39] op_sel_hi:[1,0,1]
	v_pk_fma_f32 v[40:41], v[48:49], v[16:17], v[40:41] op_sel_hi:[1,0,1]
	v_cvt_pk_f32_fp8_e32 v[42:43], v88
	v_cvt_pk_f32_fp8_sdwa v[44:45], v88 src0_sel:WORD_1
	v_pk_fma_f32 v[26:27], v[42:43], v[16:17], v[26:27] op_sel:[0,1,0] op_sel_hi:[1,1,1]
	v_pk_fma_f32 v[28:29], v[44:45], v[16:17], v[28:29] op_sel:[0,1,0] op_sel_hi:[1,1,1]
	v_cvt_pk_f32_fp8_e32 v[46:47], v89
	v_cvt_pk_f32_fp8_sdwa v[48:49], v89 src0_sel:WORD_1
	v_pk_fma_f32 v[30:31], v[46:47], v[16:17], v[30:31] op_sel:[0,1,0] op_sel_hi:[1,1,1]
	v_pk_fma_f32 v[32:33], v[48:49], v[16:17], v[32:33] op_sel:[0,1,0] op_sel_hi:[1,1,1]
	v_cvt_pk_f32_fp8_e32 v[42:43], v90
	v_cvt_pk_f32_fp8_sdwa v[44:45], v90 src0_sel:WORD_1
	v_pk_fma_f32 v[34:35], v[42:43], v[16:17], v[34:35] op_sel:[0,1,0] op_sel_hi:[1,1,1]
	v_pk_fma_f32 v[36:37], v[44:45], v[16:17], v[36:37] op_sel:[0,1,0] op_sel_hi:[1,1,1]
	v_cvt_pk_f32_fp8_e32 v[46:47], v91
	v_cvt_pk_f32_fp8_sdwa v[48:49], v91 src0_sel:WORD_1
	v_pk_fma_f32 v[38:39], v[46:47], v[16:17], v[38:39] op_sel:[0,1,0] op_sel_hi:[1,1,1]
	v_pk_fma_f32 v[40:41], v[48:49], v[16:17], v[40:41] op_sel:[0,1,0] op_sel_hi:[1,1,1]
	v_cvt_pk_f32_fp8_e32 v[42:43], v92
	v_cvt_pk_f32_fp8_sdwa v[44:45], v92 src0_sel:WORD_1
	v_pk_fma_f32 v[26:27], v[42:43], v[18:19], v[26:27] op_sel_hi:[1,0,1]
	v_pk_fma_f32 v[28:29], v[44:45], v[18:19], v[28:29] op_sel_hi:[1,0,1]
	v_cvt_pk_f32_fp8_e32 v[46:47], v93
	v_cvt_pk_f32_fp8_sdwa v[48:49], v93 src0_sel:WORD_1
	v_pk_fma_f32 v[30:31], v[46:47], v[18:19], v[30:31] op_sel_hi:[1,0,1]
	v_pk_fma_f32 v[32:33], v[48:49], v[18:19], v[32:33] op_sel_hi:[1,0,1]
	v_cvt_pk_f32_fp8_e32 v[42:43], v94
	v_cvt_pk_f32_fp8_sdwa v[44:45], v94 src0_sel:WORD_1
	v_pk_fma_f32 v[34:35], v[42:43], v[18:19], v[34:35] op_sel_hi:[1,0,1]
	v_pk_fma_f32 v[36:37], v[44:45], v[18:19], v[36:37] op_sel_hi:[1,0,1]
	v_cvt_pk_f32_fp8_e32 v[46:47], v95
	v_cvt_pk_f32_fp8_sdwa v[48:49], v95 src0_sel:WORD_1
	v_pk_fma_f32 v[38:39], v[46:47], v[18:19], v[38:39] op_sel_hi:[1,0,1]
	v_pk_fma_f32 v[40:41], v[48:49], v[18:19], v[40:41] op_sel_hi:[1,0,1]
	v_cvt_pk_f32_fp8_e32 v[42:43], v96
	v_cvt_pk_f32_fp8_sdwa v[44:45], v96 src0_sel:WORD_1
	v_pk_fma_f32 v[26:27], v[42:43], v[18:19], v[26:27] op_sel:[0,1,0] op_sel_hi:[1,1,1]
	v_pk_fma_f32 v[28:29], v[44:45], v[18:19], v[28:29] op_sel:[0,1,0] op_sel_hi:[1,1,1]
	v_cvt_pk_f32_fp8_e32 v[46:47], v97
	v_cvt_pk_f32_fp8_sdwa v[48:49], v97 src0_sel:WORD_1
	v_pk_fma_f32 v[30:31], v[46:47], v[18:19], v[30:31] op_sel:[0,1,0] op_sel_hi:[1,1,1]
	v_pk_fma_f32 v[32:33], v[48:49], v[18:19], v[32:33] op_sel:[0,1,0] op_sel_hi:[1,1,1]
	v_cvt_pk_f32_fp8_e32 v[42:43], v98
	v_cvt_pk_f32_fp8_sdwa v[44:45], v98 src0_sel:WORD_1
	v_pk_fma_f32 v[34:35], v[42:43], v[18:19], v[34:35] op_sel:[0,1,0] op_sel_hi:[1,1,1]
	v_pk_fma_f32 v[36:37], v[44:45], v[18:19], v[36:37] op_sel:[0,1,0] op_sel_hi:[1,1,1]
	v_cvt_pk_f32_fp8_e32 v[46:47], v99
	v_cvt_pk_f32_fp8_sdwa v[48:49], v99 src0_sel:WORD_1
	v_pk_fma_f32 v[38:39], v[46:47], v[18:19], v[38:39] op_sel:[0,1,0] op_sel_hi:[1,1,1]
	v_pk_fma_f32 v[40:41], v[48:49], v[18:19], v[40:41] op_sel:[0,1,0] op_sel_hi:[1,1,1]
	v_cvt_pk_f32_fp8_e32 v[42:43], v100
	v_cvt_pk_f32_fp8_sdwa v[44:45], v100 src0_sel:WORD_1
	v_pk_fma_f32 v[26:27], v[42:43], v[20:21], v[26:27] op_sel_hi:[1,0,1]
	v_pk_fma_f32 v[28:29], v[44:45], v[20:21], v[28:29] op_sel_hi:[1,0,1]
	v_cvt_pk_f32_fp8_e32 v[46:47], v101
	v_cvt_pk_f32_fp8_sdwa v[48:49], v101 src0_sel:WORD_1
	v_pk_fma_f32 v[30:31], v[46:47], v[20:21], v[30:31] op_sel_hi:[1,0,1]
	v_pk_fma_f32 v[32:33], v[48:49], v[20:21], v[32:33] op_sel_hi:[1,0,1]
	v_cvt_pk_f32_fp8_e32 v[42:43], v102
	v_cvt_pk_f32_fp8_sdwa v[44:45], v102 src0_sel:WORD_1
	v_pk_fma_f32 v[34:35], v[42:43], v[20:21], v[34:35] op_sel_hi:[1,0,1]
	v_pk_fma_f32 v[36:37], v[44:45], v[20:21], v[36:37] op_sel_hi:[1,0,1]
	v_cvt_pk_f32_fp8_e32 v[46:47], v103
	v_cvt_pk_f32_fp8_sdwa v[48:49], v103 src0_sel:WORD_1
	v_pk_fma_f32 v[38:39], v[46:47], v[20:21], v[38:39] op_sel_hi:[1,0,1]
	v_pk_fma_f32 v[40:41], v[48:49], v[20:21], v[40:41] op_sel_hi:[1,0,1]
	v_cvt_pk_f32_fp8_e32 v[42:43], v104
	v_cvt_pk_f32_fp8_sdwa v[44:45], v104 src0_sel:WORD_1
	v_pk_fma_f32 v[26:27], v[42:43], v[20:21], v[26:27] op_sel:[0,1,0] op_sel_hi:[1,1,1]
	v_pk_fma_f32 v[28:29], v[44:45], v[20:21], v[28:29] op_sel:[0,1,0] op_sel_hi:[1,1,1]
	v_cvt_pk_f32_fp8_e32 v[46:47], v105
	v_cvt_pk_f32_fp8_sdwa v[48:49], v105 src0_sel:WORD_1
	v_pk_fma_f32 v[30:31], v[46:47], v[20:21], v[30:31] op_sel:[0,1,0] op_sel_hi:[1,1,1]
	v_pk_fma_f32 v[32:33], v[48:49], v[20:21], v[32:33] op_sel:[0,1,0] op_sel_hi:[1,1,1]
	v_cvt_pk_f32_fp8_e32 v[42:43], v106
	v_cvt_pk_f32_fp8_sdwa v[44:45], v106 src0_sel:WORD_1
	v_pk_fma_f32 v[34:35], v[42:43], v[20:21], v[34:35] op_sel:[0,1,0] op_sel_hi:[1,1,1]
	v_pk_fma_f32 v[36:37], v[44:45], v[20:21], v[36:37] op_sel:[0,1,0] op_sel_hi:[1,1,1]
	v_cvt_pk_f32_fp8_e32 v[46:47], v107
	v_cvt_pk_f32_fp8_sdwa v[48:49], v107 src0_sel:WORD_1
	v_pk_fma_f32 v[38:39], v[46:47], v[20:21], v[38:39] op_sel:[0,1,0] op_sel_hi:[1,1,1]
	v_pk_fma_f32 v[40:41], v[48:49], v[20:21], v[40:41] op_sel:[0,1,0] op_sel_hi:[1,1,1]
	v_cvt_pk_f32_fp8_e32 v[42:43], v108
	v_cvt_pk_f32_fp8_sdwa v[44:45], v108 src0_sel:WORD_1
	v_pk_fma_f32 v[26:27], v[42:43], v[22:23], v[26:27] op_sel_hi:[1,0,1]
	v_pk_fma_f32 v[28:29], v[44:45], v[22:23], v[28:29] op_sel_hi:[1,0,1]
	v_cvt_pk_f32_fp8_e32 v[46:47], v109
	v_cvt_pk_f32_fp8_sdwa v[48:49], v109 src0_sel:WORD_1
	v_pk_fma_f32 v[30:31], v[46:47], v[22:23], v[30:31] op_sel_hi:[1,0,1]
	v_pk_fma_f32 v[32:33], v[48:49], v[22:23], v[32:33] op_sel_hi:[1,0,1]
	v_cvt_pk_f32_fp8_e32 v[42:43], v110
	v_cvt_pk_f32_fp8_sdwa v[44:45], v110 src0_sel:WORD_1
	v_pk_fma_f32 v[34:35], v[42:43], v[22:23], v[34:35] op_sel_hi:[1,0,1]
	v_pk_fma_f32 v[36:37], v[44:45], v[22:23], v[36:37] op_sel_hi:[1,0,1]
	v_cvt_pk_f32_fp8_e32 v[46:47], v111
	v_cvt_pk_f32_fp8_sdwa v[48:49], v111 src0_sel:WORD_1
	v_pk_fma_f32 v[38:39], v[46:47], v[22:23], v[38:39] op_sel_hi:[1,0,1]
	v_pk_fma_f32 v[40:41], v[48:49], v[22:23], v[40:41] op_sel_hi:[1,0,1]
	v_cvt_pk_f32_fp8_e32 v[42:43], v112
	v_cvt_pk_f32_fp8_sdwa v[44:45], v112 src0_sel:WORD_1
	v_pk_fma_f32 v[26:27], v[42:43], v[22:23], v[26:27] op_sel:[0,1,0] op_sel_hi:[1,1,1]
	v_pk_fma_f32 v[28:29], v[44:45], v[22:23], v[28:29] op_sel:[0,1,0] op_sel_hi:[1,1,1]
	v_cvt_pk_f32_fp8_e32 v[46:47], v113
	v_cvt_pk_f32_fp8_sdwa v[48:49], v113 src0_sel:WORD_1
	v_pk_fma_f32 v[30:31], v[46:47], v[22:23], v[30:31] op_sel:[0,1,0] op_sel_hi:[1,1,1]
	v_pk_fma_f32 v[32:33], v[48:49], v[22:23], v[32:33] op_sel:[0,1,0] op_sel_hi:[1,1,1]
	v_cvt_pk_f32_fp8_e32 v[42:43], v114
	v_cvt_pk_f32_fp8_sdwa v[44:45], v114 src0_sel:WORD_1
	v_pk_fma_f32 v[34:35], v[42:43], v[22:23], v[34:35] op_sel:[0,1,0] op_sel_hi:[1,1,1]
	v_pk_fma_f32 v[36:37], v[44:45], v[22:23], v[36:37] op_sel:[0,1,0] op_sel_hi:[1,1,1]
	v_cvt_pk_f32_fp8_e32 v[46:47], v115
	v_cvt_pk_f32_fp8_sdwa v[48:49], v115 src0_sel:WORD_1
	v_pk_fma_f32 v[38:39], v[46:47], v[22:23], v[38:39] op_sel:[0,1,0] op_sel_hi:[1,1,1]
	v_pk_fma_f32 v[40:41], v[48:49], v[22:23], v[40:41] op_sel:[0,1,0] op_sel_hi:[1,1,1]
	v_cvt_pk_f32_fp8_e32 v[42:43], v116
	v_cvt_pk_f32_fp8_sdwa v[44:45], v116 src0_sel:WORD_1
	v_pk_fma_f32 v[26:27], v[42:43], v[24:25], v[26:27] op_sel_hi:[1,0,1]
	v_pk_fma_f32 v[28:29], v[44:45], v[24:25], v[28:29] op_sel_hi:[1,0,1]
	v_cvt_pk_f32_fp8_e32 v[46:47], v117
	v_cvt_pk_f32_fp8_sdwa v[48:49], v117 src0_sel:WORD_1
	v_pk_fma_f32 v[30:31], v[46:47], v[24:25], v[30:31] op_sel_hi:[1,0,1]
	v_pk_fma_f32 v[32:33], v[48:49], v[24:25], v[32:33] op_sel_hi:[1,0,1]
	v_cvt_pk_f32_fp8_e32 v[42:43], v118
	v_cvt_pk_f32_fp8_sdwa v[44:45], v118 src0_sel:WORD_1
	v_pk_fma_f32 v[34:35], v[42:43], v[24:25], v[34:35] op_sel_hi:[1,0,1]
	v_pk_fma_f32 v[36:37], v[44:45], v[24:25], v[36:37] op_sel_hi:[1,0,1]
	v_cvt_pk_f32_fp8_e32 v[46:47], v119
	v_cvt_pk_f32_fp8_sdwa v[48:49], v119 src0_sel:WORD_1
	v_pk_fma_f32 v[38:39], v[46:47], v[24:25], v[38:39] op_sel_hi:[1,0,1]
	v_pk_fma_f32 v[40:41], v[48:49], v[24:25], v[40:41] op_sel_hi:[1,0,1]
	v_cvt_pk_f32_fp8_e32 v[42:43], v120
; __device__ __forceinline__ float wsum(float v) { v = dpp_row_sum16(v); v += __shfl_xor(v, 16); v += __shfl_xor(v, 32); return v; }
; #define P5_LOAD(A, TAB, j0)                                                                \
;   _Pragma("unroll") for (int q = 0; q < 16; q++) {                                         \
;     A[q] = ((const uint4*)((TAB) + (size_t)widx[(j0) + q] * 1024))[lane];                  \
;   }
; __device__ __forceinline__ void phase5(const Params& p, char* smem, const bool store_x = true) {
;     ...
;     for (int j0 = 0; j0 < 128; j0 += 32) {
;       P5_LOAD(A1, EV, j0 + 16)
;       P5_COMPUTE_V(A0, j0)
;       if (j0 + 32 < 128) { P5_LOAD(A0, EV, j0 + 32) }
;       P5_COMPUTE_V(A1, j0 + 16)
;     }
;     float x2[16];
; #pragma unroll
;     for (int i = 0; i < 4; i++) {
;       const float4 xv = i == 0 ? xv0 : i == 1 ? xv1 : i == 2 ? xv2 : xv3;
;       x2[4 * i] = xv.x + o2[2 * i].x; x2[4 * i + 1] = xv.y + o2[2 * i].y; x2[4 * i + 2] = xv.z + o2[2 * i + 1].x; x2[4 * i + 3] = xv.w + o2[2 * i + 1].y;
;     }
;     float ss = 0.f;
; #pragma unroll
;     for (int i = 0; i < 16; i++) ss += x2[i] * x2[i];
;     ss = wsum(ss);
;     const float rs = rsqrtf(ss * (1.f / 1024.f) + EPSF);
	v_cvt_pk_f32_fp8_sdwa v[44:45], v120 src0_sel:WORD_1
	v_pk_fma_f32 v[26:27], v[42:43], v[24:25], v[26:27] op_sel:[0,1,0] op_sel_hi:[1,1,1]
	v_pk_fma_f32 v[28:29], v[44:45], v[24:25], v[28:29] op_sel:[0,1,0] op_sel_hi:[1,1,1]
	v_cvt_pk_f32_fp8_e32 v[46:47], v121
	v_cvt_pk_f32_fp8_sdwa v[48:49], v121 src0_sel:WORD_1
	v_pk_fma_f32 v[30:31], v[46:47], v[24:25], v[30:31] op_sel:[0,1,0] op_sel_hi:[1,1,1]
	v_pk_fma_f32 v[32:33], v[48:49], v[24:25], v[32:33] op_sel:[0,1,0] op_sel_hi:[1,1,1]
	v_cvt_pk_f32_fp8_e32 v[42:43], v122
	v_cvt_pk_f32_fp8_sdwa v[44:45], v122 src0_sel:WORD_1
	v_pk_fma_f32 v[34:35], v[42:43], v[24:25], v[34:35] op_sel:[0,1,0] op_sel_hi:[1,1,1]
	v_pk_fma_f32 v[36:37], v[44:45], v[24:25], v[36:37] op_sel:[0,1,0] op_sel_hi:[1,1,1]
	v_cvt_pk_f32_fp8_e32 v[46:47], v123
	v_cvt_pk_f32_fp8_sdwa v[48:49], v123 src0_sel:WORD_1
	v_pk_fma_f32 v[38:39], v[46:47], v[24:25], v[38:39] op_sel:[0,1,0] op_sel_hi:[1,1,1]
	v_pk_fma_f32 v[40:41], v[48:49], v[24:25], v[40:41] op_sel:[0,1,0] op_sel_hi:[1,1,1]
	s_nop 1
	v_permlane32_swap_b32_e32 v26, v34
	v_permlane32_swap_b32_e32 v27, v35
	v_permlane32_swap_b32_e32 v28, v36
	v_permlane32_swap_b32_e32 v29, v37
	v_permlane32_swap_b32_e32 v30, v38
	v_permlane32_swap_b32_e32 v31, v39
	v_permlane32_swap_b32_e32 v32, v40
	v_permlane32_swap_b32_e32 v33, v41
	v_add_f32_e32 v26, v26, v34
	v_add_f32_e32 v27, v27, v35
	v_add_f32_e32 v28, v28, v36
	v_add_f32_e32 v29, v29, v37
	v_add_f32_e32 v30, v30, v38
	v_add_f32_e32 v31, v31, v39
	v_add_f32_e32 v32, v32, v40
	v_add_f32_e32 v33, v33, v41
	s_nop 1
	v_permlane16_swap_b32_e32 v26, v30
	v_permlane16_swap_b32_e32 v27, v31
	v_permlane16_swap_b32_e32 v28, v32
	v_permlane16_swap_b32_e32 v29, v33
	v_add_f32_e32 v26, v26, v30
	v_add_f32_e32 v27, v27, v31
	v_add_f32_e32 v28, v28, v32
	v_add_f32_e32 v29, v29, v33
	s_lshl_b32 s11, s12, 12
	v_add_u32_e32 v6, s11, v3
	v_add_f32_dpp v42, v26, v26 row_ror:8 row_mask:0xf bank_mask:0xf
	v_add_f32_dpp v43, v28, v28 row_ror:8 row_mask:0xf bank_mask:0xf
	v_add_f32_dpp v44, v27, v27 row_ror:8 row_mask:0xf bank_mask:0xf
	v_add_f32_dpp v45, v29, v29 row_ror:8 row_mask:0xf bank_mask:0xf
	v_cndmask_b32_e64 v46, v42, v43, s[14:15]
	v_cndmask_b32_e64 v47, v44, v45, s[14:15]
	v_add_f32_e32 v46, v50, v46
	v_add_f32_e32 v47, v51, v47
	global_store_dwordx2 v6, v[46:47], s[6:7]
	v_mul_f32_e32 v48, v46, v46
	v_fmac_f32_e32 v48, v47, v47
	s_lshl_b32 s11, s12, 2
	s_add_u32 s11, s11, 0x1100000
	v_mov_b32_e32 v7, s11
	v_add_f32_dpp v48, v48, v48 quad_perm:[1,0,3,2] row_mask:0xf bank_mask:0xf
	s_nop 1
	v_add_f32_dpp v48, v48, v48 quad_perm:[2,3,0,1] row_mask:0xf bank_mask:0xf
	s_nop 1
	v_add_f32_dpp v48, v48, v48 row_half_mirror row_mask:0xf bank_mask:0xf
	s_nop 1
	v_add_f32_dpp v48, v48, v48 row_mirror row_mask:0xf bank_mask:0xf
	s_nop 1
	v_add_f32_dpp v48, v48, v48 row_bcast:15 row_mask:0xa bank_mask:0xf
	s_nop 1
	v_add_f32_dpp v48, v48, v48 row_bcast:31 row_mask:0xc bank_mask:0xf
	s_nop 1
	s_mov_b32 exec_lo, 0
	s_brev_b32 exec_hi, 1
	global_atomic_add_f32 v7, v48, s[4:5]
	s_mov_b64 exec, -1
.Lp5v_skip0:
	s_add_u32 s10, s8, s26
	s_min_u32 s10, s10, s13
	s_lshl_b32 s18, s10, 10
	s_add_u32 s11, s16, 7
	s_and_b32 s11, s11, 7
	s_lshl_b32 s11, s11, 10
	s_add_u32 s11, s11, s17
	s_mov_b32 m0, s11
	v_lshl_add_u64 v[4:5], v[58:59], 0, s[18:19]
	global_load_lds_dwordx4 v[4:5], off
	s_add_u32 s11, s16, 3
	s_and_b32 s11, s11, 7
	s_lshl_b32 s11, s11, 10
	v_add_u32_e32 v8, s11, v2
	ds_read_b128 v[10:13], v8 offset:0
	ds_read_b128 v[14:17], v8 offset:16
	ds_read_b128 v[18:21], v8 offset:32
	ds_read_b128 v[22:25], v8 offset:48
	s_add_u32 s10, s8, s22
	s_min_u32 s10, s10, s13
	s_lshl_b32 s11, s10, 12
	v_add_u32_e32 v6, s11, v3
	global_load_dwordx2 v[50:51], v6, s[6:7]
	s_waitcnt lgkmcnt(0)
	v_add_u32_e32 v10, v10, v1
	global_load_dwordx4 v[60:63], v10, s[2:3]
	v_add_u32_e32 v11, v11, v1
	global_load_dwordx4 v[64:67], v11, s[2:3]
	v_add_u32_e32 v12, v12, v1
	global_load_dwordx4 v[68:71], v12, s[2:3]
	v_add_u32_e32 v13, v13, v1
	global_load_dwordx4 v[72:75], v13, s[2:3]
	v_add_u32_e32 v14, v14, v1
	global_load_dwordx4 v[76:79], v14, s[2:3]
	v_add_u32_e32 v15, v15, v1
	global_load_dwordx4 v[80:83], v15, s[2:3]
	v_add_u32_e32 v16, v16, v1
	global_load_dwordx4 v[84:87], v16, s[2:3]
	v_add_u32_e32 v17, v17, v1
	global_load_dwordx4 v[88:91], v17, s[2:3]
	v_add_u32_e32 v18, v18, v1
	global_load_dwordx4 v[92:95], v18, s[2:3]
	v_add_u32_e32 v19, v19, v1
	global_load_dwordx4 v[96:99], v19, s[2:3]
	v_add_u32_e32 v20, v20, v1
	global_load_dwordx4 v[100:103], v20, s[2:3]
	v_add_u32_e32 v21, v21, v1
	global_load_dwordx4 v[104:107], v21, s[2:3]
	v_add_u32_e32 v22, v22, v1
	global_load_dwordx4 v[108:111], v22, s[2:3]
	v_add_u32_e32 v23, v23, v1
	global_load_dwordx4 v[112:115], v23, s[2:3]
	v_add_u32_e32 v24, v24, v1
	global_load_dwordx4 v[116:119], v24, s[2:3]
	v_add_u32_e32 v25, v25, v1
	global_load_dwordx4 v[120:123], v25, s[2:3]
	s_add_u32 s11, s16, 1
	s_and_b32 s11, s11, 7
	s_lshl_b32 s11, s11, 10
	v_add_u32_e32 v8, s11, v2
	ds_read_b128 v[10:13], v8 offset:512
	ds_read_b128 v[14:17], v8 offset:528
	ds_read_b128 v[18:21], v8 offset:544
	ds_read_b128 v[22:25], v8 offset:560
	s_add_u32 s12, s8, s20
	s_waitcnt vmcnt(40) lgkmcnt(0)
	s_cmp_lt_u32 s12, 0x4200
	s_cbranch_scc0 .Lp5v_skip1
; #define P5_LOAD(A, TAB, j0)                                                                \
;   _Pragma("unroll") for (int q = 0; q < 16; q++) {                                         \
;     A[q] = ((const uint4*)((TAB) + (size_t)widx[(j0) + q] * 1024))[lane];                  \
;   }
; __device__ __forceinline__ void phase5(const Params& p, char* smem, const bool store_x = true) {
;     ...
;     for (int j0 = 0; j0 < 128; j0 += 32) {
;       P5_LOAD(A1, EV, j0 + 16)
;       P5_COMPUTE_V(A0, j0)
;       if (j0 + 32 < 128) { P5_LOAD(A0, EV, j0 + 32) }
;       P5_COMPUTE_V(A1, j0 + 16)
;     }
	v_cvt_pk_f32_fp8_e32 v[42:43], v124
	v_cvt_pk_f32_fp8_sdwa v[44:45], v124 src0_sel:WORD_1
	v_pk_mul_f32 v[26:27], v[42:43], v[10:11] op_sel_hi:[1,0]
	v_pk_mul_f32 v[28:29], v[44:45], v[10:11] op_sel_hi:[1,0]
	v_cvt_pk_f32_fp8_e32 v[46:47], v125
	v_cvt_pk_f32_fp8_sdwa v[48:49], v125 src0_sel:WORD_1
	v_pk_mul_f32 v[30:31], v[46:47], v[10:11] op_sel_hi:[1,0]
	v_pk_mul_f32 v[32:33], v[48:49], v[10:11] op_sel_hi:[1,0]
	v_cvt_pk_f32_fp8_e32 v[42:43], v126
	v_cvt_pk_f32_fp8_sdwa v[44:45], v126 src0_sel:WORD_1
	v_pk_mul_f32 v[34:35], v[42:43], v[10:11] op_sel_hi:[1,0]
	v_pk_mul_f32 v[36:37], v[44:45], v[10:11] op_sel_hi:[1,0]
	v_cvt_pk_f32_fp8_e32 v[46:47], v127
	v_cvt_pk_f32_fp8_sdwa v[48:49], v127 src0_sel:WORD_1
	v_pk_mul_f32 v[38:39], v[46:47], v[10:11] op_sel_hi:[1,0]
	v_pk_mul_f32 v[40:41], v[48:49], v[10:11] op_sel_hi:[1,0]
	v_cvt_pk_f32_fp8_e32 v[42:43], v128
	v_cvt_pk_f32_fp8_sdwa v[44:45], v128 src0_sel:WORD_1
	v_pk_fma_f32 v[26:27], v[42:43], v[10:11], v[26:27] op_sel:[0,1,0] op_sel_hi:[1,1,1]
	v_pk_fma_f32 v[28:29], v[44:45], v[10:11], v[28:29] op_sel:[0,1,0] op_sel_hi:[1,1,1]
	v_cvt_pk_f32_fp8_e32 v[46:47], v129
	v_cvt_pk_f32_fp8_sdwa v[48:49], v129 src0_sel:WORD_1
	v_pk_fma_f32 v[30:31], v[46:47], v[10:11], v[30:31] op_sel:[0,1,0] op_sel_hi:[1,1,1]
	v_pk_fma_f32 v[32:33], v[48:49], v[10:11], v[32:33] op_sel:[0,1,0] op_sel_hi:[1,1,1]
	v_cvt_pk_f32_fp8_e32 v[42:43], v130
	v_cvt_pk_f32_fp8_sdwa v[44:45], v130 src0_sel:WORD_1
	v_pk_fma_f32 v[34:35], v[42:43], v[10:11], v[34:35] op_sel:[0,1,0] op_sel_hi:[1,1,1]
	v_pk_fma_f32 v[36:37], v[44:45], v[10:11], v[36:37] op_sel:[0,1,0] op_sel_hi:[1,1,1]
	v_cvt_pk_f32_fp8_e32 v[46:47], v131
	v_cvt_pk_f32_fp8_sdwa v[48:49], v131 src0_sel:WORD_1
	v_pk_fma_f32 v[38:39], v[46:47], v[10:11], v[38:39] op_sel:[0,1,0] op_sel_hi:[1,1,1]
	v_pk_fma_f32 v[40:41], v[48:49], v[10:11], v[40:41] op_sel:[0,1,0] op_sel_hi:[1,1,1]
	v_cvt_pk_f32_fp8_e32 v[42:43], v132
	v_cvt_pk_f32_fp8_sdwa v[44:45], v132 src0_sel:WORD_1
	v_pk_fma_f32 v[26:27], v[42:43], v[12:13], v[26:27] op_sel_hi:[1,0,1]
	v_pk_fma_f32 v[28:29], v[44:45], v[12:13], v[28:29] op_sel_hi:[1,0,1]
	v_cvt_pk_f32_fp8_e32 v[46:47], v133
	v_cvt_pk_f32_fp8_sdwa v[48:49], v133 src0_sel:WORD_1
	v_pk_fma_f32 v[30:31], v[46:47], v[12:13], v[30:31] op_sel_hi:[1,0,1]
	v_pk_fma_f32 v[32:33], v[48:49], v[12:13], v[32:33] op_sel_hi:[1,0,1]
	v_cvt_pk_f32_fp8_e32 v[42:43], v134
	v_cvt_pk_f32_fp8_sdwa v[44:45], v134 src0_sel:WORD_1
	v_pk_fma_f32 v[34:35], v[42:43], v[12:13], v[34:35] op_sel_hi:[1,0,1]
	v_pk_fma_f32 v[36:37], v[44:45], v[12:13], v[36:37] op_sel_hi:[1,0,1]
	v_cvt_pk_f32_fp8_e32 v[46:47], v135
	v_cvt_pk_f32_fp8_sdwa v[48:49], v135 src0_sel:WORD_1
	v_pk_fma_f32 v[38:39], v[46:47], v[12:13], v[38:39] op_sel_hi:[1,0,1]
	v_pk_fma_f32 v[40:41], v[48:49], v[12:13], v[40:41] op_sel_hi:[1,0,1]
	v_cvt_pk_f32_fp8_e32 v[42:43], v136
	v_cvt_pk_f32_fp8_sdwa v[44:45], v136 src0_sel:WORD_1
	v_pk_fma_f32 v[26:27], v[42:43], v[12:13], v[26:27] op_sel:[0,1,0] op_sel_hi:[1,1,1]
	v_pk_fma_f32 v[28:29], v[44:45], v[12:13], v[28:29] op_sel:[0,1,0] op_sel_hi:[1,1,1]
	v_cvt_pk_f32_fp8_e32 v[46:47], v137
	v_cvt_pk_f32_fp8_sdwa v[48:49], v137 src0_sel:WORD_1
	v_pk_fma_f32 v[30:31], v[46:47], v[12:13], v[30:31] op_sel:[0,1,0] op_sel_hi:[1,1,1]
	v_pk_fma_f32 v[32:33], v[48:49], v[12:13], v[32:33] op_sel:[0,1,0] op_sel_hi:[1,1,1]
	v_cvt_pk_f32_fp8_e32 v[42:43], v138
	v_cvt_pk_f32_fp8_sdwa v[44:45], v138 src0_sel:WORD_1
	v_pk_fma_f32 v[34:35], v[42:43], v[12:13], v[34:35] op_sel:[0,1,0] op_sel_hi:[1,1,1]
	v_pk_fma_f32 v[36:37], v[44:45], v[12:13], v[36:37] op_sel:[0,1,0] op_sel_hi:[1,1,1]
	v_cvt_pk_f32_fp8_e32 v[46:47], v139
	v_cvt_pk_f32_fp8_sdwa v[48:49], v139 src0_sel:WORD_1
	v_pk_fma_f32 v[38:39], v[46:47], v[12:13], v[38:39] op_sel:[0,1,0] op_sel_hi:[1,1,1]
	v_pk_fma_f32 v[40:41], v[48:49], v[12:13], v[40:41] op_sel:[0,1,0] op_sel_hi:[1,1,1]
	v_cvt_pk_f32_fp8_e32 v[42:43], v140
	v_cvt_pk_f32_fp8_sdwa v[44:45], v140 src0_sel:WORD_1
	v_pk_fma_f32 v[26:27], v[42:43], v[14:15], v[26:27] op_sel_hi:[1,0,1]
	v_pk_fma_f32 v[28:29], v[44:45], v[14:15], v[28:29] op_sel_hi:[1,0,1]
	v_cvt_pk_f32_fp8_e32 v[46:47], v141
	v_cvt_pk_f32_fp8_sdwa v[48:49], v141 src0_sel:WORD_1
	v_pk_fma_f32 v[30:31], v[46:47], v[14:15], v[30:31] op_sel_hi:[1,0,1]
	v_pk_fma_f32 v[32:33], v[48:49], v[14:15], v[32:33] op_sel_hi:[1,0,1]
	v_cvt_pk_f32_fp8_e32 v[42:43], v142
	v_cvt_pk_f32_fp8_sdwa v[44:45], v142 src0_sel:WORD_1
	v_pk_fma_f32 v[34:35], v[42:43], v[14:15], v[34:35] op_sel_hi:[1,0,1]
	v_pk_fma_f32 v[36:37], v[44:45], v[14:15], v[36:37] op_sel_hi:[1,0,1]
	v_cvt_pk_f32_fp8_e32 v[46:47], v143
	v_cvt_pk_f32_fp8_sdwa v[48:49], v143 src0_sel:WORD_1
	v_pk_fma_f32 v[38:39], v[46:47], v[14:15], v[38:39] op_sel_hi:[1,0,1]
	v_pk_fma_f32 v[40:41], v[48:49], v[14:15], v[40:41] op_sel_hi:[1,0,1]
	v_cvt_pk_f32_fp8_e32 v[42:43], v144
	v_cvt_pk_f32_fp8_sdwa v[44:45], v144 src0_sel:WORD_1
	v_pk_fma_f32 v[26:27], v[42:43], v[14:15], v[26:27] op_sel:[0,1,0] op_sel_hi:[1,1,1]
	v_pk_fma_f32 v[28:29], v[44:45], v[14:15], v[28:29] op_sel:[0,1,0] op_sel_hi:[1,1,1]
	v_cvt_pk_f32_fp8_e32 v[46:47], v145
	v_cvt_pk_f32_fp8_sdwa v[48:49], v145 src0_sel:WORD_1
	v_pk_fma_f32 v[30:31], v[46:47], v[14:15], v[30:31] op_sel:[0,1,0] op_sel_hi:[1,1,1]
	v_pk_fma_f32 v[32:33], v[48:49], v[14:15], v[32:33] op_sel:[0,1,0] op_sel_hi:[1,1,1]
	v_cvt_pk_f32_fp8_e32 v[42:43], v146
	v_cvt_pk_f32_fp8_sdwa v[44:45], v146 src0_sel:WORD_1
	v_pk_fma_f32 v[34:35], v[42:43], v[14:15], v[34:35] op_sel:[0,1,0] op_sel_hi:[1,1,1]
	v_pk_fma_f32 v[36:37], v[44:45], v[14:15], v[36:37] op_sel:[0,1,0] op_sel_hi:[1,1,1]
	v_cvt_pk_f32_fp8_e32 v[46:47], v147
	v_cvt_pk_f32_fp8_sdwa v[48:49], v147 src0_sel:WORD_1
	v_pk_fma_f32 v[38:39], v[46:47], v[14:15], v[38:39] op_sel:[0,1,0] op_sel_hi:[1,1,1]
	v_pk_fma_f32 v[40:41], v[48:49], v[14:15], v[40:41] op_sel:[0,1,0] op_sel_hi:[1,1,1]
	v_cvt_pk_f32_fp8_e32 v[42:43], v148
	v_cvt_pk_f32_fp8_sdwa v[44:45], v148 src0_sel:WORD_1
	v_pk_fma_f32 v[26:27], v[42:43], v[16:17], v[26:27] op_sel_hi:[1,0,1]
	v_pk_fma_f32 v[28:29], v[44:45], v[16:17], v[28:29] op_sel_hi:[1,0,1]
	v_cvt_pk_f32_fp8_e32 v[46:47], v149
	v_cvt_pk_f32_fp8_sdwa v[48:49], v149 src0_sel:WORD_1
	v_pk_fma_f32 v[30:31], v[46:47], v[16:17], v[30:31] op_sel_hi:[1,0,1]
	v_pk_fma_f32 v[32:33], v[48:49], v[16:17], v[32:33] op_sel_hi:[1,0,1]
	v_cvt_pk_f32_fp8_e32 v[42:43], v150
	v_cvt_pk_f32_fp8_sdwa v[44:45], v150 src0_sel:WORD_1
	v_pk_fma_f32 v[34:35], v[42:43], v[16:17], v[34:35] op_sel_hi:[1,0,1]
	v_pk_fma_f32 v[36:37], v[44:45], v[16:17], v[36:37] op_sel_hi:[1,0,1]
	v_cvt_pk_f32_fp8_e32 v[46:47], v151
	v_cvt_pk_f32_fp8_sdwa v[48:49], v151 src0_sel:WORD_1
	v_pk_fma_f32 v[38:39], v[46:47], v[16:17], v[38:39] op_sel_hi:[1,0,1]
	v_pk_fma_f32 v[40:41], v[48:49], v[16:17], v[40:41] op_sel_hi:[1,0,1]
	v_cvt_pk_f32_fp8_e32 v[42:43], v152
	v_cvt_pk_f32_fp8_sdwa v[44:45], v152 src0_sel:WORD_1
	v_pk_fma_f32 v[26:27], v[42:43], v[16:17], v[26:27] op_sel:[0,1,0] op_sel_hi:[1,1,1]
	v_pk_fma_f32 v[28:29], v[44:45], v[16:17], v[28:29] op_sel:[0,1,0] op_sel_hi:[1,1,1]
	v_cvt_pk_f32_fp8_e32 v[46:47], v153
	v_cvt_pk_f32_fp8_sdwa v[48:49], v153 src0_sel:WORD_1
	v_pk_fma_f32 v[30:31], v[46:47], v[16:17], v[30:31] op_sel:[0,1,0] op_sel_hi:[1,1,1]
	v_pk_fma_f32 v[32:33], v[48:49], v[16:17], v[32:33] op_sel:[0,1,0] op_sel_hi:[1,1,1]
	v_cvt_pk_f32_fp8_e32 v[42:43], v154
	v_cvt_pk_f32_fp8_sdwa v[44:45], v154 src0_sel:WORD_1
	v_pk_fma_f32 v[34:35], v[42:43], v[16:17], v[34:35] op_sel:[0,1,0] op_sel_hi:[1,1,1]
	v_pk_fma_f32 v[36:37], v[44:45], v[16:17], v[36:37] op_sel:[0,1,0] op_sel_hi:[1,1,1]
	v_cvt_pk_f32_fp8_e32 v[46:47], v155
	v_cvt_pk_f32_fp8_sdwa v[48:49], v155 src0_sel:WORD_1
	v_pk_fma_f32 v[38:39], v[46:47], v[16:17], v[38:39] op_sel:[0,1,0] op_sel_hi:[1,1,1]
	v_pk_fma_f32 v[40:41], v[48:49], v[16:17], v[40:41] op_sel:[0,1,0] op_sel_hi:[1,1,1]
	v_cvt_pk_f32_fp8_e32 v[42:43], v156
	v_cvt_pk_f32_fp8_sdwa v[44:45], v156 src0_sel:WORD_1
	v_pk_fma_f32 v[26:27], v[42:43], v[18:19], v[26:27] op_sel_hi:[1,0,1]
	v_pk_fma_f32 v[28:29], v[44:45], v[18:19], v[28:29] op_sel_hi:[1,0,1]
	v_cvt_pk_f32_fp8_e32 v[46:47], v157
	v_cvt_pk_f32_fp8_sdwa v[48:49], v157 src0_sel:WORD_1
	v_pk_fma_f32 v[30:31], v[46:47], v[18:19], v[30:31] op_sel_hi:[1,0,1]
	v_pk_fma_f32 v[32:33], v[48:49], v[18:19], v[32:33] op_sel_hi:[1,0,1]
	v_cvt_pk_f32_fp8_e32 v[42:43], v158
	v_cvt_pk_f32_fp8_sdwa v[44:45], v158 src0_sel:WORD_1
	v_pk_fma_f32 v[34:35], v[42:43], v[18:19], v[34:35] op_sel_hi:[1,0,1]
	v_pk_fma_f32 v[36:37], v[44:45], v[18:19], v[36:37] op_sel_hi:[1,0,1]
	v_cvt_pk_f32_fp8_e32 v[46:47], v159
	v_cvt_pk_f32_fp8_sdwa v[48:49], v159 src0_sel:WORD_1
	v_pk_fma_f32 v[38:39], v[46:47], v[18:19], v[38:39] op_sel_hi:[1,0,1]
	v_pk_fma_f32 v[40:41], v[48:49], v[18:19], v[40:41] op_sel_hi:[1,0,1]
	v_cvt_pk_f32_fp8_e32 v[42:43], v160
	v_cvt_pk_f32_fp8_sdwa v[44:45], v160 src0_sel:WORD_1
	v_pk_fma_f32 v[26:27], v[42:43], v[18:19], v[26:27] op_sel:[0,1,0] op_sel_hi:[1,1,1]
	v_pk_fma_f32 v[28:29], v[44:45], v[18:19], v[28:29] op_sel:[0,1,0] op_sel_hi:[1,1,1]
	v_cvt_pk_f32_fp8_e32 v[46:47], v161
	v_cvt_pk_f32_fp8_sdwa v[48:49], v161 src0_sel:WORD_1
	v_pk_fma_f32 v[30:31], v[46:47], v[18:19], v[30:31] op_sel:[0,1,0] op_sel_hi:[1,1,1]
	v_pk_fma_f32 v[32:33], v[48:49], v[18:19], v[32:33] op_sel:[0,1,0] op_sel_hi:[1,1,1]
	v_cvt_pk_f32_fp8_e32 v[42:43], v162
	v_cvt_pk_f32_fp8_sdwa v[44:45], v162 src0_sel:WORD_1
	v_pk_fma_f32 v[34:35], v[42:43], v[18:19], v[34:35] op_sel:[0,1,0] op_sel_hi:[1,1,1]
	v_pk_fma_f32 v[36:37], v[44:45], v[18:19], v[36:37] op_sel:[0,1,0] op_sel_hi:[1,1,1]
	v_cvt_pk_f32_fp8_e32 v[46:47], v163
	v_cvt_pk_f32_fp8_sdwa v[48:49], v163 src0_sel:WORD_1
	v_pk_fma_f32 v[38:39], v[46:47], v[18:19], v[38:39] op_sel:[0,1,0] op_sel_hi:[1,1,1]
	v_pk_fma_f32 v[40:41], v[48:49], v[18:19], v[40:41] op_sel:[0,1,0] op_sel_hi:[1,1,1]
	v_cvt_pk_f32_fp8_e32 v[42:43], v164
	v_cvt_pk_f32_fp8_sdwa v[44:45], v164 src0_sel:WORD_1
	v_pk_fma_f32 v[26:27], v[42:43], v[20:21], v[26:27] op_sel_hi:[1,0,1]
	v_pk_fma_f32 v[28:29], v[44:45], v[20:21], v[28:29] op_sel_hi:[1,0,1]
	v_cvt_pk_f32_fp8_e32 v[46:47], v165
	v_cvt_pk_f32_fp8_sdwa v[48:49], v165 src0_sel:WORD_1
	v_pk_fma_f32 v[30:31], v[46:47], v[20:21], v[30:31] op_sel_hi:[1,0,1]
	v_pk_fma_f32 v[32:33], v[48:49], v[20:21], v[32:33] op_sel_hi:[1,0,1]
	v_cvt_pk_f32_fp8_e32 v[42:43], v166
	v_cvt_pk_f32_fp8_sdwa v[44:45], v166 src0_sel:WORD_1
	v_pk_fma_f32 v[34:35], v[42:43], v[20:21], v[34:35] op_sel_hi:[1,0,1]
	v_pk_fma_f32 v[36:37], v[44:45], v[20:21], v[36:37] op_sel_hi:[1,0,1]
	v_cvt_pk_f32_fp8_e32 v[46:47], v167
	v_cvt_pk_f32_fp8_sdwa v[48:49], v167 src0_sel:WORD_1
	v_pk_fma_f32 v[38:39], v[46:47], v[20:21], v[38:39] op_sel_hi:[1,0,1]
	v_pk_fma_f32 v[40:41], v[48:49], v[20:21], v[40:41] op_sel_hi:[1,0,1]
	v_cvt_pk_f32_fp8_e32 v[42:43], v168
	v_cvt_pk_f32_fp8_sdwa v[44:45], v168 src0_sel:WORD_1
	v_pk_fma_f32 v[26:27], v[42:43], v[20:21], v[26:27] op_sel:[0,1,0] op_sel_hi:[1,1,1]
	v_pk_fma_f32 v[28:29], v[44:45], v[20:21], v[28:29] op_sel:[0,1,0] op_sel_hi:[1,1,1]
	v_cvt_pk_f32_fp8_e32 v[46:47], v169
	v_cvt_pk_f32_fp8_sdwa v[48:49], v169 src0_sel:WORD_1
	v_pk_fma_f32 v[30:31], v[46:47], v[20:21], v[30:31] op_sel:[0,1,0] op_sel_hi:[1,1,1]
	v_pk_fma_f32 v[32:33], v[48:49], v[20:21], v[32:33] op_sel:[0,1,0] op_sel_hi:[1,1,1]
; __device__ __forceinline__ float wsum(float v) { v = dpp_row_sum16(v); v += __shfl_xor(v, 16); v += __shfl_xor(v, 32); return v; }
; __device__ __forceinline__ void phase5(const Params& p, char* smem, const bool store_x = true) {
;     ...
;     float x2[16];
; #pragma unroll
;     for (int i = 0; i < 4; i++) {
;       const float4 xv = i == 0 ? xv0 : i == 1 ? xv1 : i == 2 ? xv2 : xv3;
;       x2[4 * i] = xv.x + o2[2 * i].x; x2[4 * i + 1] = xv.y + o2[2 * i].y; x2[4 * i + 2] = xv.z + o2[2 * i + 1].x; x2[4 * i + 3] = xv.w + o2[2 * i + 1].y;
;     }
;     float ss = 0.f;
; #pragma unroll
;     for (int i = 0; i < 16; i++) ss += x2[i] * x2[i];
;     ss = wsum(ss);
;     const float rs = rsqrtf(ss * (1.f / 1024.f) + EPSF);
;     if (store_x) {
; #pragma unroll
;       for (int i = 0; i < 4; i++) *(float4*)(xr + i * 4) = make_float4(x2[4 * i], x2[4 * i + 1], x2[4 * i + 2], x2[4 * i + 3]);
	v_cvt_pk_f32_fp8_e32 v[42:43], v170
	v_cvt_pk_f32_fp8_sdwa v[44:45], v170 src0_sel:WORD_1
	v_pk_fma_f32 v[34:35], v[42:43], v[20:21], v[34:35] op_sel:[0,1,0] op_sel_hi:[1,1,1]
	v_pk_fma_f32 v[36:37], v[44:45], v[20:21], v[36:37] op_sel:[0,1,0] op_sel_hi:[1,1,1]
	v_cvt_pk_f32_fp8_e32 v[46:47], v171
	v_cvt_pk_f32_fp8_sdwa v[48:49], v171 src0_sel:WORD_1
	v_pk_fma_f32 v[38:39], v[46:47], v[20:21], v[38:39] op_sel:[0,1,0] op_sel_hi:[1,1,1]
	v_pk_fma_f32 v[40:41], v[48:49], v[20:21], v[40:41] op_sel:[0,1,0] op_sel_hi:[1,1,1]
	v_cvt_pk_f32_fp8_e32 v[42:43], v172
	v_cvt_pk_f32_fp8_sdwa v[44:45], v172 src0_sel:WORD_1
	v_pk_fma_f32 v[26:27], v[42:43], v[22:23], v[26:27] op_sel_hi:[1,0,1]
	v_pk_fma_f32 v[28:29], v[44:45], v[22:23], v[28:29] op_sel_hi:[1,0,1]
	v_cvt_pk_f32_fp8_e32 v[46:47], v173
	v_cvt_pk_f32_fp8_sdwa v[48:49], v173 src0_sel:WORD_1
	v_pk_fma_f32 v[30:31], v[46:47], v[22:23], v[30:31] op_sel_hi:[1,0,1]
	v_pk_fma_f32 v[32:33], v[48:49], v[22:23], v[32:33] op_sel_hi:[1,0,1]
	v_cvt_pk_f32_fp8_e32 v[42:43], v174
	v_cvt_pk_f32_fp8_sdwa v[44:45], v174 src0_sel:WORD_1
	v_pk_fma_f32 v[34:35], v[42:43], v[22:23], v[34:35] op_sel_hi:[1,0,1]
	v_pk_fma_f32 v[36:37], v[44:45], v[22:23], v[36:37] op_sel_hi:[1,0,1]
	v_cvt_pk_f32_fp8_e32 v[46:47], v175
	v_cvt_pk_f32_fp8_sdwa v[48:49], v175 src0_sel:WORD_1
	v_pk_fma_f32 v[38:39], v[46:47], v[22:23], v[38:39] op_sel_hi:[1,0,1]
	v_pk_fma_f32 v[40:41], v[48:49], v[22:23], v[40:41] op_sel_hi:[1,0,1]
	v_cvt_pk_f32_fp8_e32 v[42:43], v176
	v_cvt_pk_f32_fp8_sdwa v[44:45], v176 src0_sel:WORD_1
	v_pk_fma_f32 v[26:27], v[42:43], v[22:23], v[26:27] op_sel:[0,1,0] op_sel_hi:[1,1,1]
	v_pk_fma_f32 v[28:29], v[44:45], v[22:23], v[28:29] op_sel:[0,1,0] op_sel_hi:[1,1,1]
	v_cvt_pk_f32_fp8_e32 v[46:47], v177
	v_cvt_pk_f32_fp8_sdwa v[48:49], v177 src0_sel:WORD_1
	v_pk_fma_f32 v[30:31], v[46:47], v[22:23], v[30:31] op_sel:[0,1,0] op_sel_hi:[1,1,1]
	v_pk_fma_f32 v[32:33], v[48:49], v[22:23], v[32:33] op_sel:[0,1,0] op_sel_hi:[1,1,1]
	v_cvt_pk_f32_fp8_e32 v[42:43], v178
	v_cvt_pk_f32_fp8_sdwa v[44:45], v178 src0_sel:WORD_1
	v_pk_fma_f32 v[34:35], v[42:43], v[22:23], v[34:35] op_sel:[0,1,0] op_sel_hi:[1,1,1]
	v_pk_fma_f32 v[36:37], v[44:45], v[22:23], v[36:37] op_sel:[0,1,0] op_sel_hi:[1,1,1]
	v_cvt_pk_f32_fp8_e32 v[46:47], v179
	v_cvt_pk_f32_fp8_sdwa v[48:49], v179 src0_sel:WORD_1
	v_pk_fma_f32 v[38:39], v[46:47], v[22:23], v[38:39] op_sel:[0,1,0] op_sel_hi:[1,1,1]
	v_pk_fma_f32 v[40:41], v[48:49], v[22:23], v[40:41] op_sel:[0,1,0] op_sel_hi:[1,1,1]
	v_cvt_pk_f32_fp8_e32 v[42:43], v180
	v_cvt_pk_f32_fp8_sdwa v[44:45], v180 src0_sel:WORD_1
	v_pk_fma_f32 v[26:27], v[42:43], v[24:25], v[26:27] op_sel_hi:[1,0,1]
	v_pk_fma_f32 v[28:29], v[44:45], v[24:25], v[28:29] op_sel_hi:[1,0,1]
	v_cvt_pk_f32_fp8_e32 v[46:47], v181
	v_cvt_pk_f32_fp8_sdwa v[48:49], v181 src0_sel:WORD_1
	v_pk_fma_f32 v[30:31], v[46:47], v[24:25], v[30:31] op_sel_hi:[1,0,1]
	v_pk_fma_f32 v[32:33], v[48:49], v[24:25], v[32:33] op_sel_hi:[1,0,1]
	v_cvt_pk_f32_fp8_e32 v[42:43], v182
	v_cvt_pk_f32_fp8_sdwa v[44:45], v182 src0_sel:WORD_1
	v_pk_fma_f32 v[34:35], v[42:43], v[24:25], v[34:35] op_sel_hi:[1,0,1]
	v_pk_fma_f32 v[36:37], v[44:45], v[24:25], v[36:37] op_sel_hi:[1,0,1]
	v_cvt_pk_f32_fp8_e32 v[46:47], v183
	v_cvt_pk_f32_fp8_sdwa v[48:49], v183 src0_sel:WORD_1
	v_pk_fma_f32 v[38:39], v[46:47], v[24:25], v[38:39] op_sel_hi:[1,0,1]
	v_pk_fma_f32 v[40:41], v[48:49], v[24:25], v[40:41] op_sel_hi:[1,0,1]
	v_cvt_pk_f32_fp8_e32 v[42:43], v184
	v_cvt_pk_f32_fp8_sdwa v[44:45], v184 src0_sel:WORD_1
	v_pk_fma_f32 v[26:27], v[42:43], v[24:25], v[26:27] op_sel:[0,1,0] op_sel_hi:[1,1,1]
	v_pk_fma_f32 v[28:29], v[44:45], v[24:25], v[28:29] op_sel:[0,1,0] op_sel_hi:[1,1,1]
	v_cvt_pk_f32_fp8_e32 v[46:47], v185
	v_cvt_pk_f32_fp8_sdwa v[48:49], v185 src0_sel:WORD_1
	v_pk_fma_f32 v[30:31], v[46:47], v[24:25], v[30:31] op_sel:[0,1,0] op_sel_hi:[1,1,1]
	v_pk_fma_f32 v[32:33], v[48:49], v[24:25], v[32:33] op_sel:[0,1,0] op_sel_hi:[1,1,1]
	v_cvt_pk_f32_fp8_e32 v[42:43], v186
	v_cvt_pk_f32_fp8_sdwa v[44:45], v186 src0_sel:WORD_1
	v_pk_fma_f32 v[34:35], v[42:43], v[24:25], v[34:35] op_sel:[0,1,0] op_sel_hi:[1,1,1]
	v_pk_fma_f32 v[36:37], v[44:45], v[24:25], v[36:37] op_sel:[0,1,0] op_sel_hi:[1,1,1]
	v_cvt_pk_f32_fp8_e32 v[46:47], v187
	v_cvt_pk_f32_fp8_sdwa v[48:49], v187 src0_sel:WORD_1
	v_pk_fma_f32 v[38:39], v[46:47], v[24:25], v[38:39] op_sel:[0,1,0] op_sel_hi:[1,1,1]
	v_pk_fma_f32 v[40:41], v[48:49], v[24:25], v[40:41] op_sel:[0,1,0] op_sel_hi:[1,1,1]
	s_nop 1
	v_permlane32_swap_b32_e32 v26, v34
	v_permlane32_swap_b32_e32 v27, v35
	v_permlane32_swap_b32_e32 v28, v36
	v_permlane32_swap_b32_e32 v29, v37
	v_permlane32_swap_b32_e32 v30, v38
	v_permlane32_swap_b32_e32 v31, v39
	v_permlane32_swap_b32_e32 v32, v40
	v_permlane32_swap_b32_e32 v33, v41
	v_add_f32_e32 v26, v26, v34
	v_add_f32_e32 v27, v27, v35
	v_add_f32_e32 v28, v28, v36
	v_add_f32_e32 v29, v29, v37
	v_add_f32_e32 v30, v30, v38
	v_add_f32_e32 v31, v31, v39
	v_add_f32_e32 v32, v32, v40
	v_add_f32_e32 v33, v33, v41
	s_nop 1
	v_permlane16_swap_b32_e32 v26, v30
	v_permlane16_swap_b32_e32 v27, v31
	v_permlane16_swap_b32_e32 v28, v32
	v_permlane16_swap_b32_e32 v29, v33
	v_add_f32_e32 v26, v26, v30
	v_add_f32_e32 v27, v27, v31
	v_add_f32_e32 v28, v28, v32
	v_add_f32_e32 v29, v29, v33
	s_lshl_b32 s11, s12, 12
	v_add_u32_e32 v6, s11, v3
	v_add_f32_dpp v42, v26, v26 row_ror:8 row_mask:0xf bank_mask:0xf
	v_add_f32_dpp v43, v28, v28 row_ror:8 row_mask:0xf bank_mask:0xf
	v_add_f32_dpp v44, v27, v27 row_ror:8 row_mask:0xf bank_mask:0xf
	v_add_f32_dpp v45, v29, v29 row_ror:8 row_mask:0xf bank_mask:0xf
	v_cndmask_b32_e64 v46, v42, v43, s[14:15]
	v_cndmask_b32_e64 v47, v44, v45, s[14:15]
	v_add_f32_e32 v46, v52, v46
	v_add_f32_e32 v47, v53, v47
	global_store_dwordx2 v6, v[46:47], s[6:7]
	v_mul_f32_e32 v48, v46, v46
	v_fmac_f32_e32 v48, v47, v47
	s_lshl_b32 s11, s12, 2
	s_add_u32 s11, s11, 0x1100000
	v_mov_b32_e32 v7, s11
	v_add_f32_dpp v48, v48, v48 quad_perm:[1,0,3,2] row_mask:0xf bank_mask:0xf
	s_nop 1
	v_add_f32_dpp v48, v48, v48 quad_perm:[2,3,0,1] row_mask:0xf bank_mask:0xf
	s_nop 1
	v_add_f32_dpp v48, v48, v48 row_half_mirror row_mask:0xf bank_mask:0xf
	s_nop 1
	v_add_f32_dpp v48, v48, v48 row_mirror row_mask:0xf bank_mask:0xf
	s_nop 1
	v_add_f32_dpp v48, v48, v48 row_bcast:15 row_mask:0xa bank_mask:0xf
	s_nop 1
	v_add_f32_dpp v48, v48, v48 row_bcast:31 row_mask:0xc bank_mask:0xf
	s_nop 1
	s_mov_b32 exec_lo, 0
	s_brev_b32 exec_hi, 1
	global_atomic_add_f32 v7, v48, s[4:5]
	s_mov_b64 exec, -1
; #define P5_LOAD(A, TAB, j0)                                                                \
;   _Pragma("unroll") for (int q = 0; q < 16; q++) {                                         \
;     A[q] = ((const uint4*)((TAB) + (size_t)widx[(j0) + q] * 1024))[lane];                  \
;   }
; __device__ __forceinline__ void phase5(const Params& p, char* smem, const bool store_x = true) {
;     ...
;     for (int j0 = 0; j0 < 128; j0 += 32) {
;       P5_LOAD(A1, EV, j0 + 16)
;       P5_COMPUTE_V(A0, j0)
;       if (j0 + 32 < 128) { P5_LOAD(A0, EV, j0 + 32) }
;       P5_COMPUTE_V(A1, j0 + 16)
;     }
.Lp5v_skip1:
	s_add_u32 s10, s8, s27
	s_min_u32 s10, s10, s13
	s_lshl_b32 s18, s10, 10
	s_add_u32 s11, s16, 8
	s_and_b32 s11, s11, 7
	s_lshl_b32 s11, s11, 10
	s_add_u32 s11, s11, s17
	s_mov_b32 m0, s11
	v_lshl_add_u64 v[4:5], v[58:59], 0, s[18:19]
	global_load_lds_dwordx4 v[4:5], off
	s_add_u32 s11, s16, 4
	s_and_b32 s11, s11, 7
	s_lshl_b32 s11, s11, 10
	v_add_u32_e32 v8, s11, v2
	ds_read_b128 v[10:13], v8 offset:0
	ds_read_b128 v[14:17], v8 offset:16
	ds_read_b128 v[18:21], v8 offset:32
	ds_read_b128 v[22:25], v8 offset:48
	s_add_u32 s10, s8, s23
	s_min_u32 s10, s10, s13
	s_lshl_b32 s11, s10, 12
	v_add_u32_e32 v6, s11, v3
	global_load_dwordx2 v[52:53], v6, s[6:7]
	s_waitcnt lgkmcnt(0)
	v_add_u32_e32 v10, v10, v1
	global_load_dwordx4 v[124:127], v10, s[2:3]
	v_add_u32_e32 v11, v11, v1
	global_load_dwordx4 v[128:131], v11, s[2:3]
	v_add_u32_e32 v12, v12, v1
	global_load_dwordx4 v[132:135], v12, s[2:3]
	v_add_u32_e32 v13, v13, v1
	global_load_dwordx4 v[136:139], v13, s[2:3]
	v_add_u32_e32 v14, v14, v1
	global_load_dwordx4 v[140:143], v14, s[2:3]
	v_add_u32_e32 v15, v15, v1
	global_load_dwordx4 v[144:147], v15, s[2:3]
	v_add_u32_e32 v16, v16, v1
	global_load_dwordx4 v[148:151], v16, s[2:3]
	v_add_u32_e32 v17, v17, v1
	global_load_dwordx4 v[152:155], v17, s[2:3]
	v_add_u32_e32 v18, v18, v1
	global_load_dwordx4 v[156:159], v18, s[2:3]
	v_add_u32_e32 v19, v19, v1
	global_load_dwordx4 v[160:163], v19, s[2:3]
	v_add_u32_e32 v20, v20, v1
	global_load_dwordx4 v[164:167], v20, s[2:3]
	v_add_u32_e32 v21, v21, v1
	global_load_dwordx4 v[168:171], v21, s[2:3]
	v_add_u32_e32 v22, v22, v1
	global_load_dwordx4 v[172:175], v22, s[2:3]
	v_add_u32_e32 v23, v23, v1
	global_load_dwordx4 v[176:179], v23, s[2:3]
	v_add_u32_e32 v24, v24, v1
	global_load_dwordx4 v[180:183], v24, s[2:3]
	v_add_u32_e32 v25, v25, v1
	global_load_dwordx4 v[184:187], v25, s[2:3]
	s_add_u32 s11, s16, 2
	s_and_b32 s11, s11, 7
	s_lshl_b32 s11, s11, 10
	v_add_u32_e32 v8, s11, v2
	ds_read_b128 v[10:13], v8 offset:512
	ds_read_b128 v[14:17], v8 offset:528
	ds_read_b128 v[18:21], v8 offset:544
	ds_read_b128 v[22:25], v8 offset:560
	s_add_u32 s12, s8, s21
	s_waitcnt vmcnt(40) lgkmcnt(0)
	s_cmp_lt_u32 s12, 0x4200
	s_cbranch_scc0 .Lp5v_skip2
	v_cvt_pk_f32_fp8_e32 v[42:43], v188
	v_cvt_pk_f32_fp8_sdwa v[44:45], v188 src0_sel:WORD_1
	v_pk_mul_f32 v[26:27], v[42:43], v[10:11] op_sel_hi:[1,0]
	v_pk_mul_f32 v[28:29], v[44:45], v[10:11] op_sel_hi:[1,0]
	v_cvt_pk_f32_fp8_e32 v[46:47], v189
	v_cvt_pk_f32_fp8_sdwa v[48:49], v189 src0_sel:WORD_1
	v_pk_mul_f32 v[30:31], v[46:47], v[10:11] op_sel_hi:[1,0]
	v_pk_mul_f32 v[32:33], v[48:49], v[10:11] op_sel_hi:[1,0]
	v_cvt_pk_f32_fp8_e32 v[42:43], v190
	v_cvt_pk_f32_fp8_sdwa v[44:45], v190 src0_sel:WORD_1
	v_pk_mul_f32 v[34:35], v[42:43], v[10:11] op_sel_hi:[1,0]
	v_pk_mul_f32 v[36:37], v[44:45], v[10:11] op_sel_hi:[1,0]
	v_cvt_pk_f32_fp8_e32 v[46:47], v191
	v_cvt_pk_f32_fp8_sdwa v[48:49], v191 src0_sel:WORD_1
	v_pk_mul_f32 v[38:39], v[46:47], v[10:11] op_sel_hi:[1,0]
	v_pk_mul_f32 v[40:41], v[48:49], v[10:11] op_sel_hi:[1,0]
	v_cvt_pk_f32_fp8_e32 v[42:43], v192
	v_cvt_pk_f32_fp8_sdwa v[44:45], v192 src0_sel:WORD_1
	v_pk_fma_f32 v[26:27], v[42:43], v[10:11], v[26:27] op_sel:[0,1,0] op_sel_hi:[1,1,1]
	v_pk_fma_f32 v[28:29], v[44:45], v[10:11], v[28:29] op_sel:[0,1,0] op_sel_hi:[1,1,1]
	v_cvt_pk_f32_fp8_e32 v[46:47], v193
	v_cvt_pk_f32_fp8_sdwa v[48:49], v193 src0_sel:WORD_1
	v_pk_fma_f32 v[30:31], v[46:47], v[10:11], v[30:31] op_sel:[0,1,0] op_sel_hi:[1,1,1]
	v_pk_fma_f32 v[32:33], v[48:49], v[10:11], v[32:33] op_sel:[0,1,0] op_sel_hi:[1,1,1]
	v_cvt_pk_f32_fp8_e32 v[42:43], v194
	v_cvt_pk_f32_fp8_sdwa v[44:45], v194 src0_sel:WORD_1
	v_pk_fma_f32 v[34:35], v[42:43], v[10:11], v[34:35] op_sel:[0,1,0] op_sel_hi:[1,1,1]
	v_pk_fma_f32 v[36:37], v[44:45], v[10:11], v[36:37] op_sel:[0,1,0] op_sel_hi:[1,1,1]
	v_cvt_pk_f32_fp8_e32 v[46:47], v195
	v_cvt_pk_f32_fp8_sdwa v[48:49], v195 src0_sel:WORD_1
	v_pk_fma_f32 v[38:39], v[46:47], v[10:11], v[38:39] op_sel:[0,1,0] op_sel_hi:[1,1,1]
	v_pk_fma_f32 v[40:41], v[48:49], v[10:11], v[40:41] op_sel:[0,1,0] op_sel_hi:[1,1,1]
	v_cvt_pk_f32_fp8_e32 v[42:43], v196
	v_cvt_pk_f32_fp8_sdwa v[44:45], v196 src0_sel:WORD_1
	v_pk_fma_f32 v[26:27], v[42:43], v[12:13], v[26:27] op_sel_hi:[1,0,1]
	v_pk_fma_f32 v[28:29], v[44:45], v[12:13], v[28:29] op_sel_hi:[1,0,1]
	v_cvt_pk_f32_fp8_e32 v[46:47], v197
	v_cvt_pk_f32_fp8_sdwa v[48:49], v197 src0_sel:WORD_1
	v_pk_fma_f32 v[30:31], v[46:47], v[12:13], v[30:31] op_sel_hi:[1,0,1]
	v_pk_fma_f32 v[32:33], v[48:49], v[12:13], v[32:33] op_sel_hi:[1,0,1]
	v_cvt_pk_f32_fp8_e32 v[42:43], v198
	v_cvt_pk_f32_fp8_sdwa v[44:45], v198 src0_sel:WORD_1
	v_pk_fma_f32 v[34:35], v[42:43], v[12:13], v[34:35] op_sel_hi:[1,0,1]
	v_pk_fma_f32 v[36:37], v[44:45], v[12:13], v[36:37] op_sel_hi:[1,0,1]
	v_cvt_pk_f32_fp8_e32 v[46:47], v199
	v_cvt_pk_f32_fp8_sdwa v[48:49], v199 src0_sel:WORD_1
	v_pk_fma_f32 v[38:39], v[46:47], v[12:13], v[38:39] op_sel_hi:[1,0,1]
	v_pk_fma_f32 v[40:41], v[48:49], v[12:13], v[40:41] op_sel_hi:[1,0,1]
	v_cvt_pk_f32_fp8_e32 v[42:43], v200
	v_cvt_pk_f32_fp8_sdwa v[44:45], v200 src0_sel:WORD_1
	v_pk_fma_f32 v[26:27], v[42:43], v[12:13], v[26:27] op_sel:[0,1,0] op_sel_hi:[1,1,1]
	v_pk_fma_f32 v[28:29], v[44:45], v[12:13], v[28:29] op_sel:[0,1,0] op_sel_hi:[1,1,1]
	v_cvt_pk_f32_fp8_e32 v[46:47], v201
	v_cvt_pk_f32_fp8_sdwa v[48:49], v201 src0_sel:WORD_1
	v_pk_fma_f32 v[30:31], v[46:47], v[12:13], v[30:31] op_sel:[0,1,0] op_sel_hi:[1,1,1]
	v_pk_fma_f32 v[32:33], v[48:49], v[12:13], v[32:33] op_sel:[0,1,0] op_sel_hi:[1,1,1]
	v_cvt_pk_f32_fp8_e32 v[42:43], v202
	v_cvt_pk_f32_fp8_sdwa v[44:45], v202 src0_sel:WORD_1
	v_pk_fma_f32 v[34:35], v[42:43], v[12:13], v[34:35] op_sel:[0,1,0] op_sel_hi:[1,1,1]
	v_pk_fma_f32 v[36:37], v[44:45], v[12:13], v[36:37] op_sel:[0,1,0] op_sel_hi:[1,1,1]
	v_cvt_pk_f32_fp8_e32 v[46:47], v203
	v_cvt_pk_f32_fp8_sdwa v[48:49], v203 src0_sel:WORD_1
	v_pk_fma_f32 v[38:39], v[46:47], v[12:13], v[38:39] op_sel:[0,1,0] op_sel_hi:[1,1,1]
	v_pk_fma_f32 v[40:41], v[48:49], v[12:13], v[40:41] op_sel:[0,1,0] op_sel_hi:[1,1,1]
	v_cvt_pk_f32_fp8_e32 v[42:43], v204
	v_cvt_pk_f32_fp8_sdwa v[44:45], v204 src0_sel:WORD_1
	v_pk_fma_f32 v[26:27], v[42:43], v[14:15], v[26:27] op_sel_hi:[1,0,1]
	v_pk_fma_f32 v[28:29], v[44:45], v[14:15], v[28:29] op_sel_hi:[1,0,1]
	v_cvt_pk_f32_fp8_e32 v[46:47], v205
	v_cvt_pk_f32_fp8_sdwa v[48:49], v205 src0_sel:WORD_1
	v_pk_fma_f32 v[30:31], v[46:47], v[14:15], v[30:31] op_sel_hi:[1,0,1]
	v_pk_fma_f32 v[32:33], v[48:49], v[14:15], v[32:33] op_sel_hi:[1,0,1]
	v_cvt_pk_f32_fp8_e32 v[42:43], v206
	v_cvt_pk_f32_fp8_sdwa v[44:45], v206 src0_sel:WORD_1
	v_pk_fma_f32 v[34:35], v[42:43], v[14:15], v[34:35] op_sel_hi:[1,0,1]
	v_pk_fma_f32 v[36:37], v[44:45], v[14:15], v[36:37] op_sel_hi:[1,0,1]
	v_cvt_pk_f32_fp8_e32 v[46:47], v207
	v_cvt_pk_f32_fp8_sdwa v[48:49], v207 src0_sel:WORD_1
	v_pk_fma_f32 v[38:39], v[46:47], v[14:15], v[38:39] op_sel_hi:[1,0,1]
	v_pk_fma_f32 v[40:41], v[48:49], v[14:15], v[40:41] op_sel_hi:[1,0,1]
	v_cvt_pk_f32_fp8_e32 v[42:43], v208
	v_cvt_pk_f32_fp8_sdwa v[44:45], v208 src0_sel:WORD_1
	v_pk_fma_f32 v[26:27], v[42:43], v[14:15], v[26:27] op_sel:[0,1,0] op_sel_hi:[1,1,1]
	v_pk_fma_f32 v[28:29], v[44:45], v[14:15], v[28:29] op_sel:[0,1,0] op_sel_hi:[1,1,1]
	v_cvt_pk_f32_fp8_e32 v[46:47], v209
	v_cvt_pk_f32_fp8_sdwa v[48:49], v209 src0_sel:WORD_1
	v_pk_fma_f32 v[30:31], v[46:47], v[14:15], v[30:31] op_sel:[0,1,0] op_sel_hi:[1,1,1]
	v_pk_fma_f32 v[32:33], v[48:49], v[14:15], v[32:33] op_sel:[0,1,0] op_sel_hi:[1,1,1]
	v_cvt_pk_f32_fp8_e32 v[42:43], v210
	v_cvt_pk_f32_fp8_sdwa v[44:45], v210 src0_sel:WORD_1
	v_pk_fma_f32 v[34:35], v[42:43], v[14:15], v[34:35] op_sel:[0,1,0] op_sel_hi:[1,1,1]
	v_pk_fma_f32 v[36:37], v[44:45], v[14:15], v[36:37] op_sel:[0,1,0] op_sel_hi:[1,1,1]
	v_cvt_pk_f32_fp8_e32 v[46:47], v211
	v_cvt_pk_f32_fp8_sdwa v[48:49], v211 src0_sel:WORD_1
	v_pk_fma_f32 v[38:39], v[46:47], v[14:15], v[38:39] op_sel:[0,1,0] op_sel_hi:[1,1,1]
	v_pk_fma_f32 v[40:41], v[48:49], v[14:15], v[40:41] op_sel:[0,1,0] op_sel_hi:[1,1,1]
	v_cvt_pk_f32_fp8_e32 v[42:43], v212
	v_cvt_pk_f32_fp8_sdwa v[44:45], v212 src0_sel:WORD_1
	v_pk_fma_f32 v[26:27], v[42:43], v[16:17], v[26:27] op_sel_hi:[1,0,1]
	v_pk_fma_f32 v[28:29], v[44:45], v[16:17], v[28:29] op_sel_hi:[1,0,1]
	v_cvt_pk_f32_fp8_e32 v[46:47], v213
	v_cvt_pk_f32_fp8_sdwa v[48:49], v213 src0_sel:WORD_1
	v_pk_fma_f32 v[30:31], v[46:47], v[16:17], v[30:31] op_sel_hi:[1,0,1]
	v_pk_fma_f32 v[32:33], v[48:49], v[16:17], v[32:33] op_sel_hi:[1,0,1]
	v_cvt_pk_f32_fp8_e32 v[42:43], v214
	v_cvt_pk_f32_fp8_sdwa v[44:45], v214 src0_sel:WORD_1
	v_pk_fma_f32 v[34:35], v[42:43], v[16:17], v[34:35] op_sel_hi:[1,0,1]
	v_pk_fma_f32 v[36:37], v[44:45], v[16:17], v[36:37] op_sel_hi:[1,0,1]
	v_cvt_pk_f32_fp8_e32 v[46:47], v215
	v_cvt_pk_f32_fp8_sdwa v[48:49], v215 src0_sel:WORD_1
	v_pk_fma_f32 v[38:39], v[46:47], v[16:17], v[38:39] op_sel_hi:[1,0,1]
	v_pk_fma_f32 v[40:41], v[48:49], v[16:17], v[40:41] op_sel_hi:[1,0,1]
	v_cvt_pk_f32_fp8_e32 v[42:43], v216
	v_cvt_pk_f32_fp8_sdwa v[44:45], v216 src0_sel:WORD_1
	v_pk_fma_f32 v[26:27], v[42:43], v[16:17], v[26:27] op_sel:[0,1,0] op_sel_hi:[1,1,1]
	v_pk_fma_f32 v[28:29], v[44:45], v[16:17], v[28:29] op_sel:[0,1,0] op_sel_hi:[1,1,1]
	v_cvt_pk_f32_fp8_e32 v[46:47], v217
	v_cvt_pk_f32_fp8_sdwa v[48:49], v217 src0_sel:WORD_1
	v_pk_fma_f32 v[30:31], v[46:47], v[16:17], v[30:31] op_sel:[0,1,0] op_sel_hi:[1,1,1]
	v_pk_fma_f32 v[32:33], v[48:49], v[16:17], v[32:33] op_sel:[0,1,0] op_sel_hi:[1,1,1]
	v_cvt_pk_f32_fp8_e32 v[42:43], v218
	v_cvt_pk_f32_fp8_sdwa v[44:45], v218 src0_sel:WORD_1
	v_pk_fma_f32 v[34:35], v[42:43], v[16:17], v[34:35] op_sel:[0,1,0] op_sel_hi:[1,1,1]
	v_pk_fma_f32 v[36:37], v[44:45], v[16:17], v[36:37] op_sel:[0,1,0] op_sel_hi:[1,1,1]
	v_cvt_pk_f32_fp8_e32 v[46:47], v219
	v_cvt_pk_f32_fp8_sdwa v[48:49], v219 src0_sel:WORD_1
	v_pk_fma_f32 v[38:39], v[46:47], v[16:17], v[38:39] op_sel:[0,1,0] op_sel_hi:[1,1,1]
	v_pk_fma_f32 v[40:41], v[48:49], v[16:17], v[40:41] op_sel:[0,1,0] op_sel_hi:[1,1,1]
	v_cvt_pk_f32_fp8_e32 v[42:43], v220
	v_cvt_pk_f32_fp8_sdwa v[44:45], v220 src0_sel:WORD_1
	v_pk_fma_f32 v[26:27], v[42:43], v[18:19], v[26:27] op_sel_hi:[1,0,1]
	v_pk_fma_f32 v[28:29], v[44:45], v[18:19], v[28:29] op_sel_hi:[1,0,1]
	v_cvt_pk_f32_fp8_e32 v[46:47], v221
	v_cvt_pk_f32_fp8_sdwa v[48:49], v221 src0_sel:WORD_1
	v_pk_fma_f32 v[30:31], v[46:47], v[18:19], v[30:31] op_sel_hi:[1,0,1]
	v_pk_fma_f32 v[32:33], v[48:49], v[18:19], v[32:33] op_sel_hi:[1,0,1]
	v_cvt_pk_f32_fp8_e32 v[42:43], v222
	v_cvt_pk_f32_fp8_sdwa v[44:45], v222 src0_sel:WORD_1
	v_pk_fma_f32 v[34:35], v[42:43], v[18:19], v[34:35] op_sel_hi:[1,0,1]
	v_pk_fma_f32 v[36:37], v[44:45], v[18:19], v[36:37] op_sel_hi:[1,0,1]
	v_cvt_pk_f32_fp8_e32 v[46:47], v223
	v_cvt_pk_f32_fp8_sdwa v[48:49], v223 src0_sel:WORD_1
	v_pk_fma_f32 v[38:39], v[46:47], v[18:19], v[38:39] op_sel_hi:[1,0,1]
	v_pk_fma_f32 v[40:41], v[48:49], v[18:19], v[40:41] op_sel_hi:[1,0,1]
	v_cvt_pk_f32_fp8_e32 v[42:43], v224
	v_cvt_pk_f32_fp8_sdwa v[44:45], v224 src0_sel:WORD_1
	v_pk_fma_f32 v[26:27], v[42:43], v[18:19], v[26:27] op_sel:[0,1,0] op_sel_hi:[1,1,1]
	v_pk_fma_f32 v[28:29], v[44:45], v[18:19], v[28:29] op_sel:[0,1,0] op_sel_hi:[1,1,1]
	v_cvt_pk_f32_fp8_e32 v[46:47], v225
	v_cvt_pk_f32_fp8_sdwa v[48:49], v225 src0_sel:WORD_1
	v_pk_fma_f32 v[30:31], v[46:47], v[18:19], v[30:31] op_sel:[0,1,0] op_sel_hi:[1,1,1]
	v_pk_fma_f32 v[32:33], v[48:49], v[18:19], v[32:33] op_sel:[0,1,0] op_sel_hi:[1,1,1]
	v_cvt_pk_f32_fp8_e32 v[42:43], v226
	v_cvt_pk_f32_fp8_sdwa v[44:45], v226 src0_sel:WORD_1
	v_pk_fma_f32 v[34:35], v[42:43], v[18:19], v[34:35] op_sel:[0,1,0] op_sel_hi:[1,1,1]
	v_pk_fma_f32 v[36:37], v[44:45], v[18:19], v[36:37] op_sel:[0,1,0] op_sel_hi:[1,1,1]
	v_cvt_pk_f32_fp8_e32 v[46:47], v227
	v_cvt_pk_f32_fp8_sdwa v[48:49], v227 src0_sel:WORD_1
	v_pk_fma_f32 v[38:39], v[46:47], v[18:19], v[38:39] op_sel:[0,1,0] op_sel_hi:[1,1,1]
	v_pk_fma_f32 v[40:41], v[48:49], v[18:19], v[40:41] op_sel:[0,1,0] op_sel_hi:[1,1,1]
	v_cvt_pk_f32_fp8_e32 v[42:43], v228
	v_cvt_pk_f32_fp8_sdwa v[44:45], v228 src0_sel:WORD_1
	v_pk_fma_f32 v[26:27], v[42:43], v[20:21], v[26:27] op_sel_hi:[1,0,1]
	v_pk_fma_f32 v[28:29], v[44:45], v[20:21], v[28:29] op_sel_hi:[1,0,1]
	v_cvt_pk_f32_fp8_e32 v[46:47], v229
	v_cvt_pk_f32_fp8_sdwa v[48:49], v229 src0_sel:WORD_1
	v_pk_fma_f32 v[30:31], v[46:47], v[20:21], v[30:31] op_sel_hi:[1,0,1]
	v_pk_fma_f32 v[32:33], v[48:49], v[20:21], v[32:33] op_sel_hi:[1,0,1]
	v_cvt_pk_f32_fp8_e32 v[42:43], v230
	v_cvt_pk_f32_fp8_sdwa v[44:45], v230 src0_sel:WORD_1
	v_pk_fma_f32 v[34:35], v[42:43], v[20:21], v[34:35] op_sel_hi:[1,0,1]
	v_pk_fma_f32 v[36:37], v[44:45], v[20:21], v[36:37] op_sel_hi:[1,0,1]
	v_cvt_pk_f32_fp8_e32 v[46:47], v231
	v_cvt_pk_f32_fp8_sdwa v[48:49], v231 src0_sel:WORD_1
	v_pk_fma_f32 v[38:39], v[46:47], v[20:21], v[38:39] op_sel_hi:[1,0,1]
	v_pk_fma_f32 v[40:41], v[48:49], v[20:21], v[40:41] op_sel_hi:[1,0,1]
	v_cvt_pk_f32_fp8_e32 v[42:43], v232
	v_cvt_pk_f32_fp8_sdwa v[44:45], v232 src0_sel:WORD_1
	v_pk_fma_f32 v[26:27], v[42:43], v[20:21], v[26:27] op_sel:[0,1,0] op_sel_hi:[1,1,1]
	v_pk_fma_f32 v[28:29], v[44:45], v[20:21], v[28:29] op_sel:[0,1,0] op_sel_hi:[1,1,1]
	v_cvt_pk_f32_fp8_e32 v[46:47], v233
	v_cvt_pk_f32_fp8_sdwa v[48:49], v233 src0_sel:WORD_1
	v_pk_fma_f32 v[30:31], v[46:47], v[20:21], v[30:31] op_sel:[0,1,0] op_sel_hi:[1,1,1]
	v_pk_fma_f32 v[32:33], v[48:49], v[20:21], v[32:33] op_sel:[0,1,0] op_sel_hi:[1,1,1]
	v_cvt_pk_f32_fp8_e32 v[42:43], v234
	v_cvt_pk_f32_fp8_sdwa v[44:45], v234 src0_sel:WORD_1
	v_pk_fma_f32 v[34:35], v[42:43], v[20:21], v[34:35] op_sel:[0,1,0] op_sel_hi:[1,1,1]
	v_pk_fma_f32 v[36:37], v[44:45], v[20:21], v[36:37] op_sel:[0,1,0] op_sel_hi:[1,1,1]
	v_cvt_pk_f32_fp8_e32 v[46:47], v235
	v_cvt_pk_f32_fp8_sdwa v[48:49], v235 src0_sel:WORD_1
	v_pk_fma_f32 v[38:39], v[46:47], v[20:21], v[38:39] op_sel:[0,1,0] op_sel_hi:[1,1,1]
	v_pk_fma_f32 v[40:41], v[48:49], v[20:21], v[40:41] op_sel:[0,1,0] op_sel_hi:[1,1,1]
	v_cvt_pk_f32_fp8_e32 v[42:43], v236
	v_cvt_pk_f32_fp8_sdwa v[44:45], v236 src0_sel:WORD_1
	v_pk_fma_f32 v[26:27], v[42:43], v[22:23], v[26:27] op_sel_hi:[1,0,1]
	v_pk_fma_f32 v[28:29], v[44:45], v[22:23], v[28:29] op_sel_hi:[1,0,1]
	v_cvt_pk_f32_fp8_e32 v[46:47], v237
	v_cvt_pk_f32_fp8_sdwa v[48:49], v237 src0_sel:WORD_1
	v_pk_fma_f32 v[30:31], v[46:47], v[22:23], v[30:31] op_sel_hi:[1,0,1]
	v_pk_fma_f32 v[32:33], v[48:49], v[22:23], v[32:33] op_sel_hi:[1,0,1]
	v_cvt_pk_f32_fp8_e32 v[42:43], v238
	v_cvt_pk_f32_fp8_sdwa v[44:45], v238 src0_sel:WORD_1
	v_pk_fma_f32 v[34:35], v[42:43], v[22:23], v[34:35] op_sel_hi:[1,0,1]
	v_pk_fma_f32 v[36:37], v[44:45], v[22:23], v[36:37] op_sel_hi:[1,0,1]
	v_cvt_pk_f32_fp8_e32 v[46:47], v239
	v_cvt_pk_f32_fp8_sdwa v[48:49], v239 src0_sel:WORD_1
	v_pk_fma_f32 v[38:39], v[46:47], v[22:23], v[38:39] op_sel_hi:[1,0,1]
	v_pk_fma_f32 v[40:41], v[48:49], v[22:23], v[40:41] op_sel_hi:[1,0,1]
	v_cvt_pk_f32_fp8_e32 v[42:43], v240
	v_cvt_pk_f32_fp8_sdwa v[44:45], v240 src0_sel:WORD_1
	v_pk_fma_f32 v[26:27], v[42:43], v[22:23], v[26:27] op_sel:[0,1,0] op_sel_hi:[1,1,1]
	v_pk_fma_f32 v[28:29], v[44:45], v[22:23], v[28:29] op_sel:[0,1,0] op_sel_hi:[1,1,1]
	v_cvt_pk_f32_fp8_e32 v[46:47], v241
	v_cvt_pk_f32_fp8_sdwa v[48:49], v241 src0_sel:WORD_1
	v_pk_fma_f32 v[30:31], v[46:47], v[22:23], v[30:31] op_sel:[0,1,0] op_sel_hi:[1,1,1]
	v_pk_fma_f32 v[32:33], v[48:49], v[22:23], v[32:33] op_sel:[0,1,0] op_sel_hi:[1,1,1]
	v_cvt_pk_f32_fp8_e32 v[42:43], v242
	v_cvt_pk_f32_fp8_sdwa v[44:45], v242 src0_sel:WORD_1
	v_pk_fma_f32 v[34:35], v[42:43], v[22:23], v[34:35] op_sel:[0,1,0] op_sel_hi:[1,1,1]
	v_pk_fma_f32 v[36:37], v[44:45], v[22:23], v[36:37] op_sel:[0,1,0] op_sel_hi:[1,1,1]
; __device__ __forceinline__ float wsum(float v) { v = dpp_row_sum16(v); v += __shfl_xor(v, 16); v += __shfl_xor(v, 32); return v; }
; __device__ __forceinline__ void phase5(const Params& p, char* smem, const bool store_x = true) {
;     ...
;     float x2[16];
; #pragma unroll
;     for (int i = 0; i < 4; i++) {
;       const float4 xv = i == 0 ? xv0 : i == 1 ? xv1 : i == 2 ? xv2 : xv3;
;       x2[4 * i] = xv.x + o2[2 * i].x; x2[4 * i + 1] = xv.y + o2[2 * i].y; x2[4 * i + 2] = xv.z + o2[2 * i + 1].x; x2[4 * i + 3] = xv.w + o2[2 * i + 1].y;
;     }
;     float ss = 0.f;
; #pragma unroll
;     for (int i = 0; i < 16; i++) ss += x2[i] * x2[i];
;     ss = wsum(ss);
;     const float rs = rsqrtf(ss * (1.f / 1024.f) + EPSF);
;     if (store_x) {
; #pragma unroll
;       for (int i = 0; i < 4; i++) *(float4*)(xr + i * 4) = make_float4(x2[4 * i], x2[4 * i + 1], x2[4 * i + 2], x2[4 * i + 3]);
	v_cvt_pk_f32_fp8_e32 v[46:47], v243
	v_cvt_pk_f32_fp8_sdwa v[48:49], v243 src0_sel:WORD_1
	v_pk_fma_f32 v[38:39], v[46:47], v[22:23], v[38:39] op_sel:[0,1,0] op_sel_hi:[1,1,1]
	v_pk_fma_f32 v[40:41], v[48:49], v[22:23], v[40:41] op_sel:[0,1,0] op_sel_hi:[1,1,1]
	v_cvt_pk_f32_fp8_e32 v[42:43], v244
	v_cvt_pk_f32_fp8_sdwa v[44:45], v244 src0_sel:WORD_1
	v_pk_fma_f32 v[26:27], v[42:43], v[24:25], v[26:27] op_sel_hi:[1,0,1]
	v_pk_fma_f32 v[28:29], v[44:45], v[24:25], v[28:29] op_sel_hi:[1,0,1]
	v_cvt_pk_f32_fp8_e32 v[46:47], v245
	v_cvt_pk_f32_fp8_sdwa v[48:49], v245 src0_sel:WORD_1
	v_pk_fma_f32 v[30:31], v[46:47], v[24:25], v[30:31] op_sel_hi:[1,0,1]
	v_pk_fma_f32 v[32:33], v[48:49], v[24:25], v[32:33] op_sel_hi:[1,0,1]
	v_cvt_pk_f32_fp8_e32 v[42:43], v246
	v_cvt_pk_f32_fp8_sdwa v[44:45], v246 src0_sel:WORD_1
	v_pk_fma_f32 v[34:35], v[42:43], v[24:25], v[34:35] op_sel_hi:[1,0,1]
	v_pk_fma_f32 v[36:37], v[44:45], v[24:25], v[36:37] op_sel_hi:[1,0,1]
	v_cvt_pk_f32_fp8_e32 v[46:47], v247
	v_cvt_pk_f32_fp8_sdwa v[48:49], v247 src0_sel:WORD_1
	v_pk_fma_f32 v[38:39], v[46:47], v[24:25], v[38:39] op_sel_hi:[1,0,1]
	v_pk_fma_f32 v[40:41], v[48:49], v[24:25], v[40:41] op_sel_hi:[1,0,1]
	v_cvt_pk_f32_fp8_e32 v[42:43], v248
	v_cvt_pk_f32_fp8_sdwa v[44:45], v248 src0_sel:WORD_1
	v_pk_fma_f32 v[26:27], v[42:43], v[24:25], v[26:27] op_sel:[0,1,0] op_sel_hi:[1,1,1]
	v_pk_fma_f32 v[28:29], v[44:45], v[24:25], v[28:29] op_sel:[0,1,0] op_sel_hi:[1,1,1]
	v_cvt_pk_f32_fp8_e32 v[46:47], v249
	v_cvt_pk_f32_fp8_sdwa v[48:49], v249 src0_sel:WORD_1
	v_pk_fma_f32 v[30:31], v[46:47], v[24:25], v[30:31] op_sel:[0,1,0] op_sel_hi:[1,1,1]
	v_pk_fma_f32 v[32:33], v[48:49], v[24:25], v[32:33] op_sel:[0,1,0] op_sel_hi:[1,1,1]
	v_cvt_pk_f32_fp8_e32 v[42:43], v250
	v_cvt_pk_f32_fp8_sdwa v[44:45], v250 src0_sel:WORD_1
	v_pk_fma_f32 v[34:35], v[42:43], v[24:25], v[34:35] op_sel:[0,1,0] op_sel_hi:[1,1,1]
	v_pk_fma_f32 v[36:37], v[44:45], v[24:25], v[36:37] op_sel:[0,1,0] op_sel_hi:[1,1,1]
	v_cvt_pk_f32_fp8_e32 v[46:47], v251
	v_cvt_pk_f32_fp8_sdwa v[48:49], v251 src0_sel:WORD_1
	v_pk_fma_f32 v[38:39], v[46:47], v[24:25], v[38:39] op_sel:[0,1,0] op_sel_hi:[1,1,1]
	v_pk_fma_f32 v[40:41], v[48:49], v[24:25], v[40:41] op_sel:[0,1,0] op_sel_hi:[1,1,1]
	s_nop 1
	v_permlane32_swap_b32_e32 v26, v34
	v_permlane32_swap_b32_e32 v27, v35
	v_permlane32_swap_b32_e32 v28, v36
	v_permlane32_swap_b32_e32 v29, v37
	v_permlane32_swap_b32_e32 v30, v38
	v_permlane32_swap_b32_e32 v31, v39
	v_permlane32_swap_b32_e32 v32, v40
	v_permlane32_swap_b32_e32 v33, v41
	v_add_f32_e32 v26, v26, v34
	v_add_f32_e32 v27, v27, v35
	v_add_f32_e32 v28, v28, v36
	v_add_f32_e32 v29, v29, v37
	v_add_f32_e32 v30, v30, v38
	v_add_f32_e32 v31, v31, v39
	v_add_f32_e32 v32, v32, v40
	v_add_f32_e32 v33, v33, v41
	s_nop 1
	v_permlane16_swap_b32_e32 v26, v30
	v_permlane16_swap_b32_e32 v27, v31
	v_permlane16_swap_b32_e32 v28, v32
	v_permlane16_swap_b32_e32 v29, v33
	v_add_f32_e32 v26, v26, v30
	v_add_f32_e32 v27, v27, v31
	v_add_f32_e32 v28, v28, v32
	v_add_f32_e32 v29, v29, v33
	s_lshl_b32 s11, s12, 12
	v_add_u32_e32 v6, s11, v3
	v_add_f32_dpp v42, v26, v26 row_ror:8 row_mask:0xf bank_mask:0xf
	v_add_f32_dpp v43, v28, v28 row_ror:8 row_mask:0xf bank_mask:0xf
	v_add_f32_dpp v44, v27, v27 row_ror:8 row_mask:0xf bank_mask:0xf
	v_add_f32_dpp v45, v29, v29 row_ror:8 row_mask:0xf bank_mask:0xf
	v_cndmask_b32_e64 v46, v42, v43, s[14:15]
	v_cndmask_b32_e64 v47, v44, v45, s[14:15]
	v_add_f32_e32 v46, v54, v46
	v_add_f32_e32 v47, v55, v47
	global_store_dwordx2 v6, v[46:47], s[6:7]
	v_mul_f32_e32 v48, v46, v46
	v_fmac_f32_e32 v48, v47, v47
	s_lshl_b32 s11, s12, 2
	s_add_u32 s11, s11, 0x1100000
	v_mov_b32_e32 v7, s11
	v_add_f32_dpp v48, v48, v48 quad_perm:[1,0,3,2] row_mask:0xf bank_mask:0xf
	s_nop 1
	v_add_f32_dpp v48, v48, v48 quad_perm:[2,3,0,1] row_mask:0xf bank_mask:0xf
	s_nop 1
	v_add_f32_dpp v48, v48, v48 row_half_mirror row_mask:0xf bank_mask:0xf
	s_nop 1
	v_add_f32_dpp v48, v48, v48 row_mirror row_mask:0xf bank_mask:0xf
	s_nop 1
	v_add_f32_dpp v48, v48, v48 row_bcast:15 row_mask:0xa bank_mask:0xf
	s_nop 1
	v_add_f32_dpp v48, v48, v48 row_bcast:31 row_mask:0xc bank_mask:0xf
	s_nop 1
	s_mov_b32 exec_lo, 0
	s_brev_b32 exec_hi, 1
	global_atomic_add_f32 v7, v48, s[4:5]
	s_mov_b64 exec, -1
.Lp5v_skip2:
	s_add_u32 s8, s8, s22
	s_add_u32 s16, s16, 3
	s_cmp_lt_u32 s8, 0x4200
	s_cbranch_scc1 .Lp5v_loop
	s_waitcnt vmcnt(0)
